# mid8 stack plus split-K slab sums of the sample rows unrolled with 2-6 slabs of loads in flight (P3/P9/P11/P14/P16) and descending row order in the rowwise phases
# speedup vs baseline: 1.0048x; 1.0048x over previous
; #define GAS __attribute__((address_space(1)))
;     ...
;             if (TSRC != 0 && r >= NP) {
;                 const GAS f32x4* sp = (const GAS f32x4*)(WSP(float, WS_SLAB) + (size_t)(r - NP) * D) + lane;
; #pragma unroll
;                 for (int j = 0; j < 8; ++j) t[j] = sp[64 * j];
;                 _Pragma("unroll 1") for (int s = 1; s < nslab; ++s) { sp += (size_t)NS * D / 4;
; #pragma unroll
;                     for (int j = 0; j < 8; ++j) t[j] += sp[64 * j]; }
.LBB0_276:
	v_lshl_add_u64 v[170:171], v[142:143], 0, s[20:21]
	v_add_co_u32_e32 v182, vcc, 0x3af00000, v170
	v_add_co_u32_e64 v166, s[6:7], s17, v170
	s_nop 0
	v_addc_co_u32_e32 v183, vcc, 0, v171, vcc
	v_addc_co_u32_e64 v167, s[6:7], 0, v171, s[6:7]
	global_load_dwordx4 v[154:157], v[166:167], off
	global_load_dwordx4 v[158:161], v[166:167], off offset:1024
	global_load_dwordx4 v[162:165], v[166:167], off offset:2048
	s_nop 0
	global_load_dwordx4 v[166:169], v[166:167], off offset:3072
	s_nop 0
	global_load_dwordx4 v[170:173], v[182:183], off
	global_load_dwordx4 v[174:177], v[182:183], off offset:1024
	global_load_dwordx4 v[178:181], v[182:183], off offset:2048
	s_nop 0
	global_load_dwordx4 v[182:185], v[182:183], off offset:3072
	s_add_u32 s20, s20, 0x400000
	s_addc_u32 s21, s21, 0
	v_lshl_add_u64 v[202:203], v[142:143], 0, s[20:21]
	v_add_co_u32_e32 v214, vcc, 0x3af00000, v202
	v_add_co_u32_e64 v198, s[6:7], s17, v202
	s_nop 0
	v_addc_co_u32_e32 v215, vcc, 0, v203, vcc
	v_addc_co_u32_e64 v199, s[6:7], 0, v203, s[6:7]
	global_load_dwordx4 v[186:189], v[198:199], off
	global_load_dwordx4 v[190:193], v[198:199], off offset:1024
	global_load_dwordx4 v[194:197], v[198:199], off offset:2048
	s_nop 0
	global_load_dwordx4 v[198:201], v[198:199], off offset:3072
	s_nop 0
	global_load_dwordx4 v[202:205], v[214:215], off
	global_load_dwordx4 v[206:209], v[214:215], off offset:1024
	global_load_dwordx4 v[210:213], v[214:215], off offset:2048
	s_nop 0
	global_load_dwordx4 v[214:217], v[214:215], off offset:3072
	s_add_u32 s20, s20, 0x400000
	s_addc_u32 s21, s21, 0
	s_waitcnt vmcnt(8)
	v_pk_add_f32 v[120:121], v[120:121], v[156:157]
	v_pk_add_f32 v[118:119], v[118:119], v[154:155]
	v_pk_add_f32 v[108:109], v[108:109], v[160:161]
	v_pk_add_f32 v[106:107], v[106:107], v[158:159]
	v_pk_add_f32 v[104:105], v[104:105], v[164:165]
	v_pk_add_f32 v[102:103], v[102:103], v[162:163]
	v_pk_add_f32 v[100:101], v[100:101], v[168:169]
	v_pk_add_f32 v[98:99], v[98:99], v[166:167]
	v_pk_add_f32 v[124:125], v[124:125], v[172:173]
	v_pk_add_f32 v[122:123], v[122:123], v[170:171]
	v_pk_add_f32 v[128:129], v[128:129], v[176:177]
	v_pk_add_f32 v[126:127], v[126:127], v[174:175]
	v_pk_add_f32 v[116:117], v[116:117], v[180:181]
	v_pk_add_f32 v[114:115], v[114:115], v[178:179]
	v_pk_add_f32 v[112:113], v[112:113], v[184:185]
	v_pk_add_f32 v[110:111], v[110:111], v[182:183]
	v_lshl_add_u64 v[170:171], v[142:143], 0, s[20:21]
	v_add_co_u32_e32 v182, vcc, 0x3af00000, v170
	v_add_co_u32_e64 v166, s[6:7], s17, v170
	s_nop 0
	v_addc_co_u32_e32 v183, vcc, 0, v171, vcc
	v_addc_co_u32_e64 v167, s[6:7], 0, v171, s[6:7]
	global_load_dwordx4 v[154:157], v[166:167], off
	global_load_dwordx4 v[158:161], v[166:167], off offset:1024
	global_load_dwordx4 v[162:165], v[166:167], off offset:2048
	s_nop 0
	global_load_dwordx4 v[166:169], v[166:167], off offset:3072
	s_nop 0
	global_load_dwordx4 v[170:173], v[182:183], off
	global_load_dwordx4 v[174:177], v[182:183], off offset:1024
	global_load_dwordx4 v[178:181], v[182:183], off offset:2048
	s_nop 0
	global_load_dwordx4 v[182:185], v[182:183], off offset:3072
	s_add_u32 s20, s20, 0x400000
	s_addc_u32 s21, s21, 0
	s_waitcnt vmcnt(8)
	v_pk_add_f32 v[120:121], v[120:121], v[188:189]
	v_pk_add_f32 v[118:119], v[118:119], v[186:187]
	v_pk_add_f32 v[108:109], v[108:109], v[192:193]
	v_pk_add_f32 v[106:107], v[106:107], v[190:191]
	v_pk_add_f32 v[104:105], v[104:105], v[196:197]
	v_pk_add_f32 v[102:103], v[102:103], v[194:195]
	v_pk_add_f32 v[100:101], v[100:101], v[200:201]
	v_pk_add_f32 v[98:99], v[98:99], v[198:199]
	v_pk_add_f32 v[124:125], v[124:125], v[204:205]
	v_pk_add_f32 v[122:123], v[122:123], v[202:203]
	v_pk_add_f32 v[128:129], v[128:129], v[208:209]
	v_pk_add_f32 v[126:127], v[126:127], v[206:207]
	v_pk_add_f32 v[116:117], v[116:117], v[212:213]
	v_pk_add_f32 v[114:115], v[114:115], v[210:211]
	v_pk_add_f32 v[112:113], v[112:113], v[216:217]
	v_pk_add_f32 v[110:111], v[110:111], v[214:215]
	s_waitcnt vmcnt(0)
; #define GAS __attribute__((address_space(1)))
; __device__ __forceinline__ float bflo(unsigned w) { return __uint_as_float(w << 16); }
; __device__ __forceinline__ float bfhi(unsigned w) { return __uint_as_float(w & 0xffff0000u); }
; __device__ __forceinline__ float sigmf(float x) { return __builtin_amdgcn_rcpf(1.0f + __expf(-x)); }
; __device__ __forceinline__ float dot4(f32x4 a, f32x4 b) { return (a[0] * b[0] + a[1] * b[1]) + (a[2] * b[2] + a[3] * b[3]); }
;     ...
;                 _Pragma("unroll 1") for (int s = 1; s < nslab; ++s) { sp += (size_t)NS * D / 4;
; #pragma unroll
;                     for (int j = 0; j < 8; ++j) t[j] += sp[64 * j]; }
;                 if (TSRC == 2) { const GAS v2u* pp = (const GAS v2u*)(PUP + (size_t)r * D) + lane;
; #pragma unroll
;                     for (int j = 0; j < 8; ++j) { const v2u pw = pp[64 * j]; const f32x4 p = (f32x4){bflo(pw.x), bfhi(pw.x), bflo(pw.y), bfhi(pw.y)}; t[j] = (f32x4){sigmf(t[j][0]), sigmf(t[j][1]), sigmf(t[j][2]), sigmf(t[j][3])} * p; } }
; #pragma unroll
;                 for (int j = 0; j < 8; ++j) ss += dot4(t[j], t[j]);
	v_pk_add_f32 v[120:121], v[120:121], v[156:157]
	v_pk_add_f32 v[118:119], v[118:119], v[154:155]
	v_pk_add_f32 v[108:109], v[108:109], v[160:161]
	v_pk_add_f32 v[106:107], v[106:107], v[158:159]
	v_pk_add_f32 v[104:105], v[104:105], v[164:165]
	v_pk_add_f32 v[102:103], v[102:103], v[162:163]
	v_pk_add_f32 v[100:101], v[100:101], v[168:169]
	v_pk_add_f32 v[98:99], v[98:99], v[166:167]
	v_pk_add_f32 v[124:125], v[124:125], v[172:173]
	v_pk_add_f32 v[122:123], v[122:123], v[170:171]
	v_pk_add_f32 v[128:129], v[128:129], v[176:177]
	v_pk_add_f32 v[126:127], v[126:127], v[174:175]
	v_pk_add_f32 v[116:117], v[116:117], v[180:181]
	v_pk_add_f32 v[114:115], v[114:115], v[178:179]
	v_pk_add_f32 v[112:113], v[112:113], v[184:185]
	v_pk_add_f32 v[110:111], v[110:111], v[182:183]
	s_cmp_lg_u32 s20, 0xc00000
	v_mov_b32_e32 v154, v123
	v_mov_b32_e32 v155, v127
	v_mov_b32_e32 v142, v122
	v_mov_b32_e32 v143, v126
	v_pk_mul_f32 v[154:155], v[154:155], v[154:155]
	v_mov_b32_e32 v156, v125
	v_mov_b32_e32 v157, v129
	v_pk_fma_f32 v[142:143], v[142:143], v[142:143], v[154:155]
	v_mov_b32_e32 v154, v124
	v_mov_b32_e32 v155, v128
	v_pk_mul_f32 v[156:157], v[156:157], v[156:157]
	v_mul_f32_e32 v153, v118, v118
	v_pk_fma_f32 v[154:155], v[154:155], v[154:155], v[156:157]
	v_pk_mul_f32 v[156:157], v[114:115], v[114:115]
	v_pk_add_f32 v[142:143], v[142:143], v[154:155]
	v_pk_mul_f32 v[154:155], v[116:117], v[116:117]
	v_pk_add_f32 v[142:143], v[142:143], v[142:143] op_sel:[0,1] op_sel_hi:[1,0]
	v_pk_mov_b32 v[158:159], v[156:157], v[154:155] op_sel:[1,0]
	v_mov_b32_e32 v157, v155
	v_pk_add_f32 v[154:155], v[158:159], v[156:157]
	v_mul_f32_e32 v156, v119, v119
	v_pk_add_f32 v[154:155], v[154:155], v[154:155] op_sel:[0,1] op_sel_hi:[1,0]
	v_mov_b32_e32 v143, v153
	v_mov_b32_e32 v155, v156
	v_pk_add_f32 v[142:143], v[142:143], v[154:155]
	v_mul_f32_e32 v154, v111, v111
	v_mul_f32_e32 v157, v120, v120
	v_pk_fma_f32 v[154:155], v[110:111], v[110:111], v[154:155] op_sel_hi:[1,1,0]
	v_mul_f32_e32 v156, v113, v113
	v_mul_f32_e32 v158, v121, v121
	v_mov_b32_e32 v155, v157
	v_pk_fma_f32 v[156:157], v[112:113], v[112:113], v[156:157] op_sel_hi:[1,1,0]
	v_mul_f32_e32 v153, v98, v98
	v_mov_b32_e32 v157, v158
	v_pk_add_f32 v[154:155], v[154:155], v[156:157]
	v_pk_mul_f32 v[156:157], v[106:107], v[106:107]
	v_pk_add_f32 v[142:143], v[142:143], v[154:155]
	v_pk_mul_f32 v[154:155], v[108:109], v[108:109]
	v_pk_add_f32 v[142:143], v[142:143], v[142:143] op_sel:[0,1] op_sel_hi:[1,0]
	v_pk_mov_b32 v[158:159], v[156:157], v[154:155] op_sel:[1,0]
	v_mov_b32_e32 v157, v155
	v_pk_add_f32 v[154:155], v[158:159], v[156:157]
	v_mul_f32_e32 v156, v99, v99
	v_pk_add_f32 v[154:155], v[154:155], v[154:155] op_sel:[0,1] op_sel_hi:[1,0]
	v_mov_b32_e32 v143, v153
	v_mov_b32_e32 v155, v156
	v_pk_add_f32 v[142:143], v[142:143], v[154:155]
	v_mul_f32_e32 v154, v103, v103
	v_mul_f32_e32 v157, v100, v100
	v_pk_fma_f32 v[154:155], v[102:103], v[102:103], v[154:155] op_sel_hi:[1,1,0]
	v_mul_f32_e32 v156, v105, v105
	v_mul_f32_e32 v158, v101, v101
	v_mov_b32_e32 v155, v157
	v_pk_fma_f32 v[156:157], v[104:105], v[104:105], v[156:157] op_sel_hi:[1,1,0]
	s_nop 0
	v_mov_b32_e32 v157, v158
	v_pk_add_f32 v[154:155], v[154:155], v[156:157]
	s_nop 0
	v_pk_add_f32 v[142:143], v[142:143], v[154:155]
	s_nop 0
	v_add_f32_e32 v142, v142, v143
	s_branch .LBB0_271

; #define GAS __attribute__((address_space(1)))
; __device__ __forceinline__ void mixfix_all(Frame& F, int nslab) {
;     ...
;     for (int r = gw; r < NS; r += NGW) {
;         const GAS f32x4* sp = (const GAS f32x4*)(WSP(float, WS_SLAB) + (size_t)r * D) + lane; f32x4 t[8];
; #pragma unroll
;         for (int j = 0; j < 8; ++j) t[j] = sp[64 * j];
;         _Pragma("unroll 1") for (int s = 1; s < nslab; ++s) { sp += (size_t)NS * D / 4;
; #pragma unroll
;             for (int j = 0; j < 8; ++j) t[j] += sp[64 * j]; }
.LBB0_1306:
	v_lshl_add_u64 v[40:41], v[38:39], 0, s[14:15]
	v_add_co_u32_e32 v52, vcc, s3, v40
	s_add_u32 s14, s14, 0x400000
	s_nop 0
	v_addc_co_u32_e32 v53, vcc, 0, v41, vcc
	s_waitcnt lgkmcnt(0)
	v_add_co_u32_e32 v68, vcc, s5, v40
	s_addc_u32 s15, s15, 0
	s_nop 0
	v_addc_co_u32_e32 v69, vcc, 0, v41, vcc
	global_load_dwordx4 v[40:43], v[68:69], off offset:-4096
	global_load_dwordx4 v[44:47], v[52:53], off offset:1024
	global_load_dwordx4 v[48:51], v[52:53], off offset:2048
	s_nop 0
	global_load_dwordx4 v[52:55], v[52:53], off offset:3072
	s_nop 0
	global_load_dwordx4 v[56:59], v[68:69], off
	global_load_dwordx4 v[60:63], v[68:69], off offset:1024
	global_load_dwordx4 v[64:67], v[68:69], off offset:2048
	s_nop 0
	global_load_dwordx4 v[68:71], v[68:69], off offset:3072
	v_lshl_add_u64 v[72:73], v[38:39], 0, s[14:15]
	v_add_co_u32_e32 v84, vcc, s3, v72
	s_add_u32 s14, s14, 0x400000
	s_nop 0
	v_addc_co_u32_e32 v85, vcc, 0, v73, vcc
	s_waitcnt lgkmcnt(0)
	v_add_co_u32_e32 v100, vcc, s5, v72
	s_addc_u32 s15, s15, 0
	s_nop 0
	v_addc_co_u32_e32 v101, vcc, 0, v73, vcc
	global_load_dwordx4 v[72:75], v[100:101], off offset:-4096
	global_load_dwordx4 v[76:79], v[84:85], off offset:1024
	global_load_dwordx4 v[80:83], v[84:85], off offset:2048
	s_nop 0
	global_load_dwordx4 v[84:87], v[84:85], off offset:3072
	s_nop 0
	global_load_dwordx4 v[88:91], v[100:101], off
	global_load_dwordx4 v[92:95], v[100:101], off offset:1024
	global_load_dwordx4 v[96:99], v[100:101], off offset:2048
	s_nop 0
	global_load_dwordx4 v[100:103], v[100:101], off offset:3072
	v_lshl_add_u64 v[104:105], v[38:39], 0, s[14:15]
	v_add_co_u32_e32 v116, vcc, s3, v104
	s_add_u32 s14, s14, 0x400000
	s_nop 0
	v_addc_co_u32_e32 v117, vcc, 0, v105, vcc
	s_waitcnt lgkmcnt(0)
	v_add_co_u32_e32 v132, vcc, s5, v104
	s_addc_u32 s15, s15, 0
	s_nop 0
	v_addc_co_u32_e32 v133, vcc, 0, v105, vcc
	global_load_dwordx4 v[104:107], v[132:133], off offset:-4096
	global_load_dwordx4 v[108:111], v[116:117], off offset:1024
	global_load_dwordx4 v[112:115], v[116:117], off offset:2048
	s_nop 0
	global_load_dwordx4 v[116:119], v[116:117], off offset:3072
	s_nop 0
	global_load_dwordx4 v[120:123], v[132:133], off
	global_load_dwordx4 v[124:127], v[132:133], off offset:1024
	global_load_dwordx4 v[128:131], v[132:133], off offset:2048
	s_nop 0
	global_load_dwordx4 v[132:135], v[132:133], off offset:3072
	v_lshl_add_u64 v[146:147], v[38:39], 0, s[14:15]
	v_add_co_u32_e32 v158, vcc, s3, v146
	s_add_u32 s14, s14, 0x400000
	s_nop 0
	v_addc_co_u32_e32 v159, vcc, 0, v147, vcc
	s_waitcnt lgkmcnt(0)
	v_add_co_u32_e32 v174, vcc, s5, v146
	s_addc_u32 s15, s15, 0
	s_nop 0
	v_addc_co_u32_e32 v175, vcc, 0, v147, vcc
	global_load_dwordx4 v[146:149], v[174:175], off offset:-4096
	global_load_dwordx4 v[150:153], v[158:159], off offset:1024
	global_load_dwordx4 v[154:157], v[158:159], off offset:2048
	s_nop 0
	global_load_dwordx4 v[158:161], v[158:159], off offset:3072
	s_nop 0
	global_load_dwordx4 v[162:165], v[174:175], off
	global_load_dwordx4 v[166:169], v[174:175], off offset:1024
	global_load_dwordx4 v[170:173], v[174:175], off offset:2048
	s_nop 0
	global_load_dwordx4 v[174:177], v[174:175], off offset:3072
	v_lshl_add_u64 v[178:179], v[38:39], 0, s[14:15]
	v_add_co_u32_e32 v190, vcc, s3, v178
	s_add_u32 s14, s14, 0x400000
	s_nop 0
	v_addc_co_u32_e32 v191, vcc, 0, v179, vcc
	s_waitcnt lgkmcnt(0)
	v_add_co_u32_e32 v206, vcc, s5, v178
	s_addc_u32 s15, s15, 0
	s_nop 0
	v_addc_co_u32_e32 v207, vcc, 0, v179, vcc
	global_load_dwordx4 v[178:181], v[206:207], off offset:-4096
	global_load_dwordx4 v[182:185], v[190:191], off offset:1024
	global_load_dwordx4 v[186:189], v[190:191], off offset:2048
	s_nop 0
	global_load_dwordx4 v[190:193], v[190:191], off offset:3072
	s_nop 0
	global_load_dwordx4 v[194:197], v[206:207], off
	global_load_dwordx4 v[198:201], v[206:207], off offset:1024
	global_load_dwordx4 v[202:205], v[206:207], off offset:2048
	s_nop 0
	global_load_dwordx4 v[206:209], v[206:207], off offset:3072
	v_lshl_add_u64 v[210:211], v[38:39], 0, s[14:15]
	v_add_co_u32_e32 v222, vcc, s3, v210
	s_add_u32 s14, s14, 0x400000
	s_nop 0
	v_addc_co_u32_e32 v223, vcc, 0, v211, vcc
	s_waitcnt lgkmcnt(0)
	v_add_co_u32_e32 v238, vcc, s5, v210
	s_addc_u32 s15, s15, 0
	s_nop 0
	v_addc_co_u32_e32 v239, vcc, 0, v211, vcc
	global_load_dwordx4 v[210:213], v[238:239], off offset:-4096
	global_load_dwordx4 v[214:217], v[222:223], off offset:1024
	global_load_dwordx4 v[218:221], v[222:223], off offset:2048
	s_nop 0
	global_load_dwordx4 v[222:225], v[222:223], off offset:3072
	s_nop 0
	global_load_dwordx4 v[226:229], v[238:239], off
	global_load_dwordx4 v[230:233], v[238:239], off offset:1024
	global_load_dwordx4 v[234:237], v[238:239], off offset:2048
	s_nop 0
	global_load_dwordx4 v[238:241], v[238:239], off offset:3072
	s_waitcnt vmcnt(40)
	v_pk_add_f32 v[32:33], v[32:33], v[42:43]
	v_pk_add_f32 v[30:31], v[30:31], v[40:41]
	v_pk_add_f32 v[28:29], v[28:29], v[46:47]
	v_pk_add_f32 v[26:27], v[26:27], v[44:45]
	v_pk_add_f32 v[24:25], v[24:25], v[50:51]
	v_pk_add_f32 v[22:23], v[22:23], v[48:49]
	v_pk_add_f32 v[20:21], v[20:21], v[54:55]
	v_pk_add_f32 v[18:19], v[18:19], v[52:53]
	v_pk_add_f32 v[16:17], v[16:17], v[58:59]
	v_pk_add_f32 v[14:15], v[14:15], v[56:57]
	v_pk_add_f32 v[12:13], v[12:13], v[62:63]
	v_pk_add_f32 v[10:11], v[10:11], v[60:61]
	v_pk_add_f32 v[8:9], v[8:9], v[66:67]
	v_pk_add_f32 v[6:7], v[6:7], v[64:65]
	v_pk_add_f32 v[4:5], v[4:5], v[70:71]
	v_pk_add_f32 v[2:3], v[2:3], v[68:69]
	v_lshl_add_u64 v[40:41], v[38:39], 0, s[14:15]
	v_add_co_u32_e32 v52, vcc, s3, v40
	s_add_u32 s14, s14, 0x400000
	s_nop 0
	v_addc_co_u32_e32 v53, vcc, 0, v41, vcc
	s_waitcnt lgkmcnt(0)
; __device__ __forceinline__ void mixfix_all(Frame& F, int nslab) {
;     ...
;         for (int j = 0; j < 8; ++j) t[j] = sp[64 * j];
;         _Pragma("unroll 1") for (int s = 1; s < nslab; ++s) { sp += (size_t)NS * D / 4;
; #pragma unroll
;             for (int j = 0; j < 8; ++j) t[j] += sp[64 * j]; }
	v_add_co_u32_e32 v68, vcc, s5, v40
	s_addc_u32 s15, s15, 0
	s_nop 0
	v_addc_co_u32_e32 v69, vcc, 0, v41, vcc
	global_load_dwordx4 v[40:43], v[68:69], off offset:-4096
	global_load_dwordx4 v[44:47], v[52:53], off offset:1024
	global_load_dwordx4 v[48:51], v[52:53], off offset:2048
	s_nop 0
	global_load_dwordx4 v[52:55], v[52:53], off offset:3072
	s_nop 0
	global_load_dwordx4 v[56:59], v[68:69], off
	global_load_dwordx4 v[60:63], v[68:69], off offset:1024
	global_load_dwordx4 v[64:67], v[68:69], off offset:2048
	s_nop 0
	global_load_dwordx4 v[68:71], v[68:69], off offset:3072
	s_waitcnt vmcnt(40)
	v_pk_add_f32 v[32:33], v[32:33], v[74:75]
	v_pk_add_f32 v[30:31], v[30:31], v[72:73]
	v_pk_add_f32 v[28:29], v[28:29], v[78:79]
	v_pk_add_f32 v[26:27], v[26:27], v[76:77]
	v_pk_add_f32 v[24:25], v[24:25], v[82:83]
	v_pk_add_f32 v[22:23], v[22:23], v[80:81]
	v_pk_add_f32 v[20:21], v[20:21], v[86:87]
	v_pk_add_f32 v[18:19], v[18:19], v[84:85]
	v_pk_add_f32 v[16:17], v[16:17], v[90:91]
	v_pk_add_f32 v[14:15], v[14:15], v[88:89]
	v_pk_add_f32 v[12:13], v[12:13], v[94:95]
	v_pk_add_f32 v[10:11], v[10:11], v[92:93]
	v_pk_add_f32 v[8:9], v[8:9], v[98:99]
	v_pk_add_f32 v[6:7], v[6:7], v[96:97]
	v_pk_add_f32 v[4:5], v[4:5], v[102:103]
	v_pk_add_f32 v[2:3], v[2:3], v[100:101]
	s_waitcnt vmcnt(32)
	v_pk_add_f32 v[32:33], v[32:33], v[106:107]
	v_pk_add_f32 v[30:31], v[30:31], v[104:105]
	v_pk_add_f32 v[28:29], v[28:29], v[110:111]
	v_pk_add_f32 v[26:27], v[26:27], v[108:109]
	v_pk_add_f32 v[24:25], v[24:25], v[114:115]
	v_pk_add_f32 v[22:23], v[22:23], v[112:113]
	v_pk_add_f32 v[20:21], v[20:21], v[118:119]
	v_pk_add_f32 v[18:19], v[18:19], v[116:117]
	v_pk_add_f32 v[16:17], v[16:17], v[122:123]
	v_pk_add_f32 v[14:15], v[14:15], v[120:121]
	v_pk_add_f32 v[12:13], v[12:13], v[126:127]
	v_pk_add_f32 v[10:11], v[10:11], v[124:125]
	v_pk_add_f32 v[8:9], v[8:9], v[130:131]
	v_pk_add_f32 v[6:7], v[6:7], v[128:129]
	v_pk_add_f32 v[4:5], v[4:5], v[134:135]
	v_pk_add_f32 v[2:3], v[2:3], v[132:133]
	s_waitcnt vmcnt(24)
	v_pk_add_f32 v[32:33], v[32:33], v[148:149]
	v_pk_add_f32 v[30:31], v[30:31], v[146:147]
	v_pk_add_f32 v[28:29], v[28:29], v[152:153]
	v_pk_add_f32 v[26:27], v[26:27], v[150:151]
	v_pk_add_f32 v[24:25], v[24:25], v[156:157]
	v_pk_add_f32 v[22:23], v[22:23], v[154:155]
	v_pk_add_f32 v[20:21], v[20:21], v[160:161]
	v_pk_add_f32 v[18:19], v[18:19], v[158:159]
	v_pk_add_f32 v[16:17], v[16:17], v[164:165]
	v_pk_add_f32 v[14:15], v[14:15], v[162:163]
	v_pk_add_f32 v[12:13], v[12:13], v[168:169]
	v_pk_add_f32 v[10:11], v[10:11], v[166:167]
	v_pk_add_f32 v[8:9], v[8:9], v[172:173]
	v_pk_add_f32 v[6:7], v[6:7], v[170:171]
	v_pk_add_f32 v[4:5], v[4:5], v[176:177]
	v_pk_add_f32 v[2:3], v[2:3], v[174:175]
	s_waitcnt vmcnt(16)
	v_pk_add_f32 v[32:33], v[32:33], v[180:181]
	v_pk_add_f32 v[30:31], v[30:31], v[178:179]
	v_pk_add_f32 v[28:29], v[28:29], v[184:185]
	v_pk_add_f32 v[26:27], v[26:27], v[182:183]
	v_pk_add_f32 v[24:25], v[24:25], v[188:189]
	v_pk_add_f32 v[22:23], v[22:23], v[186:187]
	v_pk_add_f32 v[20:21], v[20:21], v[192:193]
	v_pk_add_f32 v[18:19], v[18:19], v[190:191]
	v_pk_add_f32 v[16:17], v[16:17], v[196:197]
	v_pk_add_f32 v[14:15], v[14:15], v[194:195]
	v_pk_add_f32 v[12:13], v[12:13], v[200:201]
	v_pk_add_f32 v[10:11], v[10:11], v[198:199]
	v_pk_add_f32 v[8:9], v[8:9], v[204:205]
	v_pk_add_f32 v[6:7], v[6:7], v[202:203]
	v_pk_add_f32 v[4:5], v[4:5], v[208:209]
	v_pk_add_f32 v[2:3], v[2:3], v[206:207]
	s_waitcnt vmcnt(8)
	v_pk_add_f32 v[32:33], v[32:33], v[212:213]
	v_pk_add_f32 v[30:31], v[30:31], v[210:211]
	v_pk_add_f32 v[28:29], v[28:29], v[216:217]
	v_pk_add_f32 v[26:27], v[26:27], v[214:215]
	v_pk_add_f32 v[24:25], v[24:25], v[220:221]
	v_pk_add_f32 v[22:23], v[22:23], v[218:219]
	v_pk_add_f32 v[20:21], v[20:21], v[224:225]
	v_pk_add_f32 v[18:19], v[18:19], v[222:223]
	v_pk_add_f32 v[16:17], v[16:17], v[228:229]
	v_pk_add_f32 v[14:15], v[14:15], v[226:227]
	v_pk_add_f32 v[12:13], v[12:13], v[232:233]
	v_pk_add_f32 v[10:11], v[10:11], v[230:231]
	v_pk_add_f32 v[8:9], v[8:9], v[236:237]
	v_pk_add_f32 v[6:7], v[6:7], v[234:235]
	v_pk_add_f32 v[4:5], v[4:5], v[240:241]
	v_pk_add_f32 v[2:3], v[2:3], v[238:239]
	s_waitcnt vmcnt(0)
; #define GAS __attribute__((address_space(1)))
; __device__ __forceinline__ unsigned pk2(float lo, float hi) { return f2bf(lo) | (f2bf(hi) << 16); }
; __device__ __forceinline__ void mixfix_all(Frame& F, int nslab) {
;     ...
;         _Pragma("unroll 1") for (int s = 1; s < nslab; ++s) { sp += (size_t)NS * D / 4;
; #pragma unroll
;             for (int j = 0; j < 8; ++j) t[j] += sp[64 * j]; }
; #pragma unroll
;         for (int j = 0; j < 8; ++j) { v2u w; w.x = pk2(t[j][0], t[j][1]); w.y = pk2(t[j][2], t[j][3]); ((GAS v2u*)(MIX + (size_t)(NP + r) * D))[lane + 64 * j] = w; }
;     }
	v_pk_add_f32 v[32:33], v[32:33], v[42:43]
	v_pk_add_f32 v[30:31], v[30:31], v[40:41]
	v_pk_add_f32 v[28:29], v[28:29], v[46:47]
	v_pk_add_f32 v[26:27], v[26:27], v[44:45]
	v_pk_add_f32 v[24:25], v[24:25], v[50:51]
	v_pk_add_f32 v[22:23], v[22:23], v[48:49]
	v_pk_add_f32 v[20:21], v[20:21], v[54:55]
	v_pk_add_f32 v[18:19], v[18:19], v[52:53]
	v_pk_add_f32 v[16:17], v[16:17], v[58:59]
	v_pk_add_f32 v[14:15], v[14:15], v[56:57]
	v_pk_add_f32 v[12:13], v[12:13], v[62:63]
	v_pk_add_f32 v[10:11], v[10:11], v[60:61]
	v_pk_add_f32 v[8:9], v[8:9], v[66:67]
	v_pk_add_f32 v[6:7], v[6:7], v[64:65]
	v_pk_add_f32 v[4:5], v[4:5], v[70:71]
	v_pk_add_f32 v[2:3], v[2:3], v[68:69]
	s_cmp_eq_u32 s14, 0x1c00000
	v_bfe_u32 v40, v30, 16, 1
	v_add3_u32 v30, v30, v40, s16
	v_bfe_u32 v40, v31, 16, 1
	v_lshrrev_b32_e32 v30, 16, v30
	v_add3_u32 v31, v31, v40, s16
	v_and_or_b32 v30, v31, s17, v30
	v_bfe_u32 v31, v32, 16, 1
	v_add3_u32 v31, v32, v31, s16
	v_bfe_u32 v32, v33, 16, 1
	s_lshl_b64 s[14:15], s[0:1], 12
	v_lshrrev_b32_e32 v31, 16, v31
	v_add3_u32 v32, v33, v32, s16
	v_and_or_b32 v31, v32, s17, v31
	v_lshl_add_u64 v[32:33], v[36:37], 0, s[14:15]
	v_lshl_add_u64 v[40:41], v[32:33], 0, s[12:13]
	v_add_co_u32_e32 v32, vcc, s18, v32
	s_add_i32 s0, s0, s4
	s_nop 0
	v_addc_co_u32_e32 v33, vcc, 0, v33, vcc
	global_store_dwordx2 v[32:33], v[30:31], off
	v_bfe_u32 v30, v26, 16, 1
	v_add3_u32 v26, v26, v30, s16
	v_bfe_u32 v30, v27, 16, 1
	v_lshrrev_b32_e32 v26, 16, v26
	v_add3_u32 v27, v27, v30, s16
	v_and_or_b32 v26, v27, s17, v26
	v_bfe_u32 v27, v28, 16, 1
	v_add3_u32 v27, v28, v27, s16
	v_bfe_u32 v28, v29, 16, 1
	v_lshrrev_b32_e32 v27, 16, v27
	v_add3_u32 v28, v29, v28, s16
	v_and_or_b32 v27, v28, s17, v27
	global_store_dwordx2 v[40:41], v[26:27], off offset:512
	v_bfe_u32 v26, v22, 16, 1
	v_add3_u32 v22, v22, v26, s16
	v_bfe_u32 v26, v23, 16, 1
	v_lshrrev_b32_e32 v22, 16, v22
	v_add3_u32 v23, v23, v26, s16
	v_and_or_b32 v22, v23, s17, v22
	v_bfe_u32 v23, v24, 16, 1
	v_add3_u32 v23, v24, v23, s16
	v_bfe_u32 v24, v25, 16, 1
	v_lshrrev_b32_e32 v23, 16, v23
	v_add3_u32 v24, v25, v24, s16
	v_and_or_b32 v23, v24, s17, v23
	global_store_dwordx2 v[40:41], v[22:23], off offset:1024
	v_bfe_u32 v22, v18, 16, 1
	v_add3_u32 v18, v18, v22, s16
	v_bfe_u32 v22, v19, 16, 1
	v_lshrrev_b32_e32 v18, 16, v18
	v_add3_u32 v19, v19, v22, s16
	v_and_or_b32 v18, v19, s17, v18
	v_bfe_u32 v19, v20, 16, 1
	v_add3_u32 v19, v20, v19, s16
	v_bfe_u32 v20, v21, 16, 1
	v_lshrrev_b32_e32 v19, 16, v19
	v_add3_u32 v20, v21, v20, s16
	v_and_or_b32 v19, v20, s17, v19
	global_store_dwordx2 v[40:41], v[18:19], off offset:1536
	v_bfe_u32 v18, v14, 16, 1
	v_add3_u32 v14, v14, v18, s16
	v_bfe_u32 v18, v15, 16, 1
	v_lshrrev_b32_e32 v14, 16, v14
	v_add3_u32 v15, v15, v18, s16
	v_and_or_b32 v14, v15, s17, v14
	v_bfe_u32 v15, v16, 16, 1
	v_add3_u32 v15, v16, v15, s16
	v_bfe_u32 v16, v17, 16, 1
	v_lshrrev_b32_e32 v15, 16, v15
	v_add3_u32 v16, v17, v16, s16
	v_and_or_b32 v15, v16, s17, v15
	global_store_dwordx2 v[40:41], v[14:15], off offset:2048
	v_bfe_u32 v14, v10, 16, 1
	v_add3_u32 v10, v10, v14, s16
	v_bfe_u32 v14, v11, 16, 1
	v_lshrrev_b32_e32 v10, 16, v10
	v_add3_u32 v11, v11, v14, s16
	v_and_or_b32 v10, v11, s17, v10
	v_bfe_u32 v11, v12, 16, 1
	v_add3_u32 v11, v12, v11, s16
	v_bfe_u32 v12, v13, 16, 1
	v_lshrrev_b32_e32 v11, 16, v11
	v_add3_u32 v12, v13, v12, s16
	v_and_or_b32 v11, v12, s17, v11
	global_store_dwordx2 v[40:41], v[10:11], off offset:2560
	v_bfe_u32 v10, v6, 16, 1
	v_add3_u32 v6, v6, v10, s16
	v_bfe_u32 v10, v7, 16, 1
	v_lshrrev_b32_e32 v6, 16, v6
	v_add3_u32 v7, v7, v10, s16
	v_and_or_b32 v6, v7, s17, v6
	v_bfe_u32 v7, v8, 16, 1
	v_add3_u32 v7, v8, v7, s16
	v_bfe_u32 v8, v9, 16, 1
	v_lshrrev_b32_e32 v7, 16, v7
	v_add3_u32 v8, v9, v8, s16
	v_and_or_b32 v7, v8, s17, v7
	global_store_dwordx2 v[40:41], v[6:7], off offset:3072
	v_bfe_u32 v6, v2, 16, 1
	v_add3_u32 v2, v2, v6, s16
	v_bfe_u32 v6, v3, 16, 1
	v_lshrrev_b32_e32 v2, 16, v2
	v_add3_u32 v3, v3, v6, s16
	v_and_or_b32 v2, v3, s17, v2
	v_bfe_u32 v3, v4, 16, 1
	v_add3_u32 v3, v4, v3, s16
	v_bfe_u32 v4, v5, 16, 1
	v_lshrrev_b32_e32 v3, 16, v3
	v_add3_u32 v4, v5, v4, s16
	v_and_or_b32 v3, v4, s17, v3
	s_cmpk_gt_i32 s0, 0x1ff
	v_lshl_add_u64 v[38:39], v[38:39], 0, s[10:11]
	global_store_dwordx2 v[40:41], v[2:3], off offset:3584
	s_cbranch_scc0 .LBB0_1305

; #define GAS __attribute__((address_space(1)))
;     ...
;                 const GAS f32x4* sp = (const GAS f32x4*)(WSP(float, WS_SLAB) + (size_t)(r - NP) * D) + lane;
; #pragma unroll
;                 for (int j = 0; j < 8; ++j) t[j] = sp[64 * j];
;                 _Pragma("unroll 1") for (int s = 1; s < nslab; ++s) { sp += (size_t)NS * D / 4;
; #pragma unroll
;                     for (int j = 0; j < 8; ++j) t[j] += sp[64 * j]; }
.LBB0_1491:
	v_lshl_add_u64 v[152:153], v[124:125], 0, s[14:15]
	v_add_co_u32_e32 v164, vcc, 0x3af00000, v152
	v_add_co_u32_e64 v148, s[0:1], s17, v152
	s_nop 0
	v_addc_co_u32_e32 v165, vcc, 0, v153, vcc
	v_addc_co_u32_e64 v149, s[0:1], 0, v153, s[0:1]
	global_load_dwordx4 v[136:139], v[148:149], off
	global_load_dwordx4 v[140:143], v[148:149], off offset:1024
	global_load_dwordx4 v[144:147], v[148:149], off offset:2048
	s_nop 0
	global_load_dwordx4 v[148:151], v[148:149], off offset:3072
	s_nop 0
	global_load_dwordx4 v[152:155], v[164:165], off
	global_load_dwordx4 v[156:159], v[164:165], off offset:1024
	global_load_dwordx4 v[160:163], v[164:165], off offset:2048
	s_nop 0
	global_load_dwordx4 v[164:167], v[164:165], off offset:3072
	s_add_u32 s14, s14, 0x400000
	s_addc_u32 s15, s15, 0
	v_lshl_add_u64 v[184:185], v[124:125], 0, s[14:15]
	v_add_co_u32_e32 v196, vcc, 0x3af00000, v184
	v_add_co_u32_e64 v180, s[0:1], s17, v184
	s_nop 0
	v_addc_co_u32_e32 v197, vcc, 0, v185, vcc
	v_addc_co_u32_e64 v181, s[0:1], 0, v185, s[0:1]
	global_load_dwordx4 v[168:171], v[180:181], off
	global_load_dwordx4 v[172:175], v[180:181], off offset:1024
	global_load_dwordx4 v[176:179], v[180:181], off offset:2048
	s_nop 0
	global_load_dwordx4 v[180:183], v[180:181], off offset:3072
	s_nop 0
	global_load_dwordx4 v[184:187], v[196:197], off
	global_load_dwordx4 v[188:191], v[196:197], off offset:1024
	global_load_dwordx4 v[192:195], v[196:197], off offset:2048
	s_nop 0
	global_load_dwordx4 v[196:199], v[196:197], off offset:3072
	s_add_u32 s14, s14, 0x400000
	s_addc_u32 s15, s15, 0
	v_lshl_add_u64 v[216:217], v[124:125], 0, s[14:15]
	v_add_co_u32_e32 v228, vcc, 0x3af00000, v216
	v_add_co_u32_e64 v212, s[0:1], s17, v216
	s_nop 0
	v_addc_co_u32_e32 v229, vcc, 0, v217, vcc
	v_addc_co_u32_e64 v213, s[0:1], 0, v217, s[0:1]
	global_load_dwordx4 v[200:203], v[212:213], off
	global_load_dwordx4 v[204:207], v[212:213], off offset:1024
	global_load_dwordx4 v[208:211], v[212:213], off offset:2048
	s_nop 0
	global_load_dwordx4 v[212:215], v[212:213], off offset:3072
	s_nop 0
	global_load_dwordx4 v[216:219], v[228:229], off
	global_load_dwordx4 v[220:223], v[228:229], off offset:1024
	global_load_dwordx4 v[224:227], v[228:229], off offset:2048
	s_nop 0
	global_load_dwordx4 v[228:231], v[228:229], off offset:3072
	s_add_u32 s14, s14, 0x400000
	s_addc_u32 s15, s15, 0
	s_waitcnt vmcnt(16)
	v_pk_add_f32 v[84:85], v[84:85], v[138:139]
	v_pk_add_f32 v[82:83], v[82:83], v[136:137]
	v_pk_add_f32 v[76:77], v[76:77], v[142:143]
	v_pk_add_f32 v[74:75], v[74:75], v[140:141]
	v_pk_add_f32 v[72:73], v[72:73], v[146:147]
	v_pk_add_f32 v[70:71], v[70:71], v[144:145]
	v_pk_add_f32 v[68:69], v[68:69], v[150:151]
	v_pk_add_f32 v[66:67], v[66:67], v[148:149]
	v_pk_add_f32 v[92:93], v[92:93], v[154:155]
	v_pk_add_f32 v[90:91], v[90:91], v[152:153]
	v_pk_add_f32 v[96:97], v[96:97], v[158:159]
	v_pk_add_f32 v[94:95], v[94:95], v[156:157]
	v_pk_add_f32 v[88:89], v[88:89], v[162:163]
	v_pk_add_f32 v[86:87], v[86:87], v[160:161]
	v_pk_add_f32 v[80:81], v[80:81], v[166:167]
	v_pk_add_f32 v[78:79], v[78:79], v[164:165]
	v_lshl_add_u64 v[152:153], v[124:125], 0, s[14:15]
	v_add_co_u32_e32 v164, vcc, 0x3af00000, v152
	v_add_co_u32_e64 v148, s[0:1], s17, v152
	s_nop 0
	v_addc_co_u32_e32 v165, vcc, 0, v153, vcc
	v_addc_co_u32_e64 v149, s[0:1], 0, v153, s[0:1]
	global_load_dwordx4 v[136:139], v[148:149], off
	global_load_dwordx4 v[140:143], v[148:149], off offset:1024
	global_load_dwordx4 v[144:147], v[148:149], off offset:2048
	s_nop 0
	global_load_dwordx4 v[148:151], v[148:149], off offset:3072
	s_nop 0
	global_load_dwordx4 v[152:155], v[164:165], off
	global_load_dwordx4 v[156:159], v[164:165], off offset:1024
	global_load_dwordx4 v[160:163], v[164:165], off offset:2048
	s_nop 0
	global_load_dwordx4 v[164:167], v[164:165], off offset:3072
	s_add_u32 s14, s14, 0x400000
	s_addc_u32 s15, s15, 0
	s_waitcnt vmcnt(16)
	v_pk_add_f32 v[84:85], v[84:85], v[170:171]
	v_pk_add_f32 v[82:83], v[82:83], v[168:169]
	v_pk_add_f32 v[76:77], v[76:77], v[174:175]
	v_pk_add_f32 v[74:75], v[74:75], v[172:173]
	v_pk_add_f32 v[72:73], v[72:73], v[178:179]
	v_pk_add_f32 v[70:71], v[70:71], v[176:177]
	v_pk_add_f32 v[68:69], v[68:69], v[182:183]
	v_pk_add_f32 v[66:67], v[66:67], v[180:181]
	v_pk_add_f32 v[92:93], v[92:93], v[186:187]
	v_pk_add_f32 v[90:91], v[90:91], v[184:185]
	v_pk_add_f32 v[96:97], v[96:97], v[190:191]
	v_pk_add_f32 v[94:95], v[94:95], v[188:189]
	v_pk_add_f32 v[88:89], v[88:89], v[194:195]
	v_pk_add_f32 v[86:87], v[86:87], v[192:193]
	v_pk_add_f32 v[80:81], v[80:81], v[198:199]
	v_pk_add_f32 v[78:79], v[78:79], v[196:197]
	v_lshl_add_u64 v[184:185], v[124:125], 0, s[14:15]
	v_add_co_u32_e32 v196, vcc, 0x3af00000, v184
	v_add_co_u32_e64 v180, s[0:1], s17, v184
	s_nop 0
	v_addc_co_u32_e32 v197, vcc, 0, v185, vcc
	v_addc_co_u32_e64 v181, s[0:1], 0, v185, s[0:1]
	global_load_dwordx4 v[168:171], v[180:181], off
	global_load_dwordx4 v[172:175], v[180:181], off offset:1024
	global_load_dwordx4 v[176:179], v[180:181], off offset:2048
	s_nop 0
	global_load_dwordx4 v[180:183], v[180:181], off offset:3072
	s_nop 0
	global_load_dwordx4 v[184:187], v[196:197], off
	global_load_dwordx4 v[188:191], v[196:197], off offset:1024
	global_load_dwordx4 v[192:195], v[196:197], off offset:2048
	s_nop 0
	global_load_dwordx4 v[196:199], v[196:197], off offset:3072
	s_add_u32 s14, s14, 0x400000
	s_addc_u32 s15, s15, 0
	s_waitcnt vmcnt(16)
;     ...
;                 _Pragma("unroll 1") for (int s = 1; s < nslab; ++s) { sp += (size_t)NS * D / 4;
; #pragma unroll
;                     for (int j = 0; j < 8; ++j) t[j] += sp[64 * j]; }
	v_pk_add_f32 v[84:85], v[84:85], v[202:203]
	v_pk_add_f32 v[82:83], v[82:83], v[200:201]
	v_pk_add_f32 v[76:77], v[76:77], v[206:207]
	v_pk_add_f32 v[74:75], v[74:75], v[204:205]
	v_pk_add_f32 v[72:73], v[72:73], v[210:211]
	v_pk_add_f32 v[70:71], v[70:71], v[208:209]
	v_pk_add_f32 v[68:69], v[68:69], v[214:215]
	v_pk_add_f32 v[66:67], v[66:67], v[212:213]
	v_pk_add_f32 v[92:93], v[92:93], v[218:219]
	v_pk_add_f32 v[90:91], v[90:91], v[216:217]
	v_pk_add_f32 v[96:97], v[96:97], v[222:223]
	v_pk_add_f32 v[94:95], v[94:95], v[220:221]
	v_pk_add_f32 v[88:89], v[88:89], v[226:227]
	v_pk_add_f32 v[86:87], v[86:87], v[224:225]
	v_pk_add_f32 v[80:81], v[80:81], v[230:231]
	v_pk_add_f32 v[78:79], v[78:79], v[228:229]
	v_lshl_add_u64 v[216:217], v[124:125], 0, s[14:15]
	v_add_co_u32_e32 v228, vcc, 0x3af00000, v216
	v_add_co_u32_e64 v212, s[0:1], s17, v216
	s_nop 0
	v_addc_co_u32_e32 v229, vcc, 0, v217, vcc
	v_addc_co_u32_e64 v213, s[0:1], 0, v217, s[0:1]
	global_load_dwordx4 v[200:203], v[212:213], off
	global_load_dwordx4 v[204:207], v[212:213], off offset:1024
	global_load_dwordx4 v[208:211], v[212:213], off offset:2048
	s_nop 0
	global_load_dwordx4 v[212:215], v[212:213], off offset:3072
	s_nop 0
	global_load_dwordx4 v[216:219], v[228:229], off
	global_load_dwordx4 v[220:223], v[228:229], off offset:1024
	global_load_dwordx4 v[224:227], v[228:229], off offset:2048
	s_nop 0
	global_load_dwordx4 v[228:231], v[228:229], off offset:3072
	s_add_u32 s14, s14, 0x400000
	s_addc_u32 s15, s15, 0
	s_waitcnt vmcnt(16)
	v_pk_add_f32 v[84:85], v[84:85], v[138:139]
	v_pk_add_f32 v[82:83], v[82:83], v[136:137]
	v_pk_add_f32 v[76:77], v[76:77], v[142:143]
	v_pk_add_f32 v[74:75], v[74:75], v[140:141]
	v_pk_add_f32 v[72:73], v[72:73], v[146:147]
	v_pk_add_f32 v[70:71], v[70:71], v[144:145]
	v_pk_add_f32 v[68:69], v[68:69], v[150:151]
	v_pk_add_f32 v[66:67], v[66:67], v[148:149]
	v_pk_add_f32 v[92:93], v[92:93], v[154:155]
	v_pk_add_f32 v[90:91], v[90:91], v[152:153]
	v_pk_add_f32 v[96:97], v[96:97], v[158:159]
	v_pk_add_f32 v[94:95], v[94:95], v[156:157]
	v_pk_add_f32 v[88:89], v[88:89], v[162:163]
	v_pk_add_f32 v[86:87], v[86:87], v[160:161]
	v_pk_add_f32 v[80:81], v[80:81], v[166:167]
	v_pk_add_f32 v[78:79], v[78:79], v[164:165]
	v_lshl_add_u64 v[152:153], v[124:125], 0, s[14:15]
	v_add_co_u32_e32 v164, vcc, 0x3af00000, v152
	v_add_co_u32_e64 v148, s[0:1], s17, v152
	s_nop 0
	v_addc_co_u32_e32 v165, vcc, 0, v153, vcc
	v_addc_co_u32_e64 v149, s[0:1], 0, v153, s[0:1]
	global_load_dwordx4 v[136:139], v[148:149], off
	global_load_dwordx4 v[140:143], v[148:149], off offset:1024
	global_load_dwordx4 v[144:147], v[148:149], off offset:2048
	s_nop 0
	global_load_dwordx4 v[148:151], v[148:149], off offset:3072
	s_nop 0
	global_load_dwordx4 v[152:155], v[164:165], off
	global_load_dwordx4 v[156:159], v[164:165], off offset:1024
	global_load_dwordx4 v[160:163], v[164:165], off offset:2048
	s_nop 0
	global_load_dwordx4 v[164:167], v[164:165], off offset:3072
	s_add_u32 s14, s14, 0x400000
	s_addc_u32 s15, s15, 0
	s_waitcnt vmcnt(16)
	v_pk_add_f32 v[84:85], v[84:85], v[170:171]
	v_pk_add_f32 v[82:83], v[82:83], v[168:169]
	v_pk_add_f32 v[76:77], v[76:77], v[174:175]
	v_pk_add_f32 v[74:75], v[74:75], v[172:173]
	v_pk_add_f32 v[72:73], v[72:73], v[178:179]
	v_pk_add_f32 v[70:71], v[70:71], v[176:177]
	v_pk_add_f32 v[68:69], v[68:69], v[182:183]
	v_pk_add_f32 v[66:67], v[66:67], v[180:181]
	v_pk_add_f32 v[92:93], v[92:93], v[186:187]
	v_pk_add_f32 v[90:91], v[90:91], v[184:185]
	v_pk_add_f32 v[96:97], v[96:97], v[190:191]
	v_pk_add_f32 v[94:95], v[94:95], v[188:189]
	v_pk_add_f32 v[88:89], v[88:89], v[194:195]
	v_pk_add_f32 v[86:87], v[86:87], v[192:193]
	v_pk_add_f32 v[80:81], v[80:81], v[198:199]
	v_pk_add_f32 v[78:79], v[78:79], v[196:197]
	s_waitcnt vmcnt(8)
; #define GAS __attribute__((address_space(1)))
; __device__ __forceinline__ float bflo(unsigned w) { return __uint_as_float(w << 16); }
; __device__ __forceinline__ float bfhi(unsigned w) { return __uint_as_float(w & 0xffff0000u); }
; __device__ __forceinline__ float sigmf(float x) { return __builtin_amdgcn_rcpf(1.0f + __expf(-x)); }
; __device__ __forceinline__ float dot4(f32x4 a, f32x4 b) { return (a[0] * b[0] + a[1] * b[1]) + (a[2] * b[2] + a[3] * b[3]); }
;     ...
;                 _Pragma("unroll 1") for (int s = 1; s < nslab; ++s) { sp += (size_t)NS * D / 4;
; #pragma unroll
;                     for (int j = 0; j < 8; ++j) t[j] += sp[64 * j]; }
;                 if (TSRC == 2) { const GAS v2u* pp = (const GAS v2u*)(PUP + (size_t)r * D) + lane;
; #pragma unroll
;                     for (int j = 0; j < 8; ++j) { const v2u pw = pp[64 * j]; const f32x4 p = (f32x4){bflo(pw.x), bfhi(pw.x), bflo(pw.y), bfhi(pw.y)}; t[j] = (f32x4){sigmf(t[j][0]), sigmf(t[j][1]), sigmf(t[j][2]), sigmf(t[j][3])} * p; } }
; #pragma unroll
;                 for (int j = 0; j < 8; ++j) ss += dot4(t[j], t[j]);
	v_pk_add_f32 v[84:85], v[84:85], v[202:203]
	v_pk_add_f32 v[82:83], v[82:83], v[200:201]
	v_pk_add_f32 v[76:77], v[76:77], v[206:207]
	v_pk_add_f32 v[74:75], v[74:75], v[204:205]
	v_pk_add_f32 v[72:73], v[72:73], v[210:211]
	v_pk_add_f32 v[70:71], v[70:71], v[208:209]
	v_pk_add_f32 v[68:69], v[68:69], v[214:215]
	v_pk_add_f32 v[66:67], v[66:67], v[212:213]
	v_pk_add_f32 v[92:93], v[92:93], v[218:219]
	v_pk_add_f32 v[90:91], v[90:91], v[216:217]
	v_pk_add_f32 v[96:97], v[96:97], v[222:223]
	v_pk_add_f32 v[94:95], v[94:95], v[220:221]
	v_pk_add_f32 v[88:89], v[88:89], v[226:227]
	v_pk_add_f32 v[86:87], v[86:87], v[224:225]
	v_pk_add_f32 v[80:81], v[80:81], v[230:231]
	v_pk_add_f32 v[78:79], v[78:79], v[228:229]
	s_waitcnt vmcnt(0)
	v_pk_add_f32 v[84:85], v[84:85], v[138:139]
	v_pk_add_f32 v[82:83], v[82:83], v[136:137]
	v_pk_add_f32 v[76:77], v[76:77], v[142:143]
	v_pk_add_f32 v[74:75], v[74:75], v[140:141]
	v_pk_add_f32 v[72:73], v[72:73], v[146:147]
	v_pk_add_f32 v[70:71], v[70:71], v[144:145]
	v_pk_add_f32 v[68:69], v[68:69], v[150:151]
	v_pk_add_f32 v[66:67], v[66:67], v[148:149]
	v_pk_add_f32 v[92:93], v[92:93], v[154:155]
	v_pk_add_f32 v[90:91], v[90:91], v[152:153]
	v_pk_add_f32 v[96:97], v[96:97], v[158:159]
	v_pk_add_f32 v[94:95], v[94:95], v[156:157]
	v_pk_add_f32 v[88:89], v[88:89], v[162:163]
	v_pk_add_f32 v[86:87], v[86:87], v[160:161]
	v_pk_add_f32 v[80:81], v[80:81], v[166:167]
	v_pk_add_f32 v[78:79], v[78:79], v[164:165]
	s_cmp_lg_u32 s14, 0x1c00000
	v_mov_b32_e32 v136, v91
	v_mov_b32_e32 v137, v95
	v_mov_b32_e32 v124, v90
	v_mov_b32_e32 v125, v94
	v_pk_mul_f32 v[136:137], v[136:137], v[136:137]
	v_mov_b32_e32 v138, v93
	v_mov_b32_e32 v139, v97
	v_pk_fma_f32 v[124:125], v[124:125], v[124:125], v[136:137]
	v_mov_b32_e32 v136, v92
	v_mov_b32_e32 v137, v96
	v_pk_mul_f32 v[138:139], v[138:139], v[138:139]
	v_mul_f32_e32 v135, v82, v82
	v_pk_fma_f32 v[136:137], v[136:137], v[136:137], v[138:139]
	v_pk_mul_f32 v[138:139], v[86:87], v[86:87]
	v_pk_add_f32 v[124:125], v[124:125], v[136:137]
	v_pk_mul_f32 v[136:137], v[88:89], v[88:89]
	v_pk_add_f32 v[124:125], v[124:125], v[124:125] op_sel:[0,1] op_sel_hi:[1,0]
	v_pk_mov_b32 v[140:141], v[138:139], v[136:137] op_sel:[1,0]
	v_mov_b32_e32 v139, v137
	v_pk_add_f32 v[136:137], v[140:141], v[138:139]
	v_mul_f32_e32 v138, v83, v83
	v_pk_add_f32 v[136:137], v[136:137], v[136:137] op_sel:[0,1] op_sel_hi:[1,0]
	v_mov_b32_e32 v125, v135
	v_mov_b32_e32 v137, v138
	v_pk_add_f32 v[124:125], v[124:125], v[136:137]
	v_mul_f32_e32 v136, v79, v79
	v_mul_f32_e32 v139, v84, v84
	v_pk_fma_f32 v[136:137], v[78:79], v[78:79], v[136:137] op_sel_hi:[1,1,0]
	v_mul_f32_e32 v138, v81, v81
	v_mul_f32_e32 v140, v85, v85
	v_mov_b32_e32 v137, v139
	v_pk_fma_f32 v[138:139], v[80:81], v[80:81], v[138:139] op_sel_hi:[1,1,0]
	v_mul_f32_e32 v135, v66, v66
	v_mov_b32_e32 v139, v140
	v_pk_add_f32 v[136:137], v[136:137], v[138:139]
	v_pk_mul_f32 v[138:139], v[74:75], v[74:75]
	v_pk_add_f32 v[124:125], v[124:125], v[136:137]
	v_pk_mul_f32 v[136:137], v[76:77], v[76:77]
	v_pk_add_f32 v[124:125], v[124:125], v[124:125] op_sel:[0,1] op_sel_hi:[1,0]
	v_pk_mov_b32 v[140:141], v[138:139], v[136:137] op_sel:[1,0]
	v_mov_b32_e32 v139, v137
	v_pk_add_f32 v[136:137], v[140:141], v[138:139]
	v_mul_f32_e32 v138, v67, v67
	v_pk_add_f32 v[136:137], v[136:137], v[136:137] op_sel:[0,1] op_sel_hi:[1,0]
	v_mov_b32_e32 v125, v135
	v_mov_b32_e32 v137, v138
	v_pk_add_f32 v[124:125], v[124:125], v[136:137]
	v_mul_f32_e32 v136, v71, v71
	v_mul_f32_e32 v139, v68, v68
	v_pk_fma_f32 v[136:137], v[70:71], v[70:71], v[136:137] op_sel_hi:[1,1,0]
	v_mul_f32_e32 v138, v73, v73
	v_mul_f32_e32 v140, v69, v69
	v_mov_b32_e32 v137, v139
	v_pk_fma_f32 v[138:139], v[72:73], v[72:73], v[138:139] op_sel_hi:[1,1,0]
	s_nop 0
	v_mov_b32_e32 v139, v140
	v_pk_add_f32 v[136:137], v[136:137], v[138:139]
	s_nop 0
	v_pk_add_f32 v[124:125], v[124:125], v[136:137]
	s_nop 0
	v_add_f32_e32 v124, v124, v125
	s_branch .LBB0_1486

; #define GAS __attribute__((address_space(1)))
;     ...
;                 const GAS f32x4* sp = (const GAS f32x4*)(WSP(float, WS_SLAB) + (size_t)(r - NP) * D) + lane;
; #pragma unroll
;                 for (int j = 0; j < 8; ++j) t[j] = sp[64 * j];
;                 _Pragma("unroll 1") for (int s = 1; s < nslab; ++s) { sp += (size_t)NS * D / 4;
; #pragma unroll
;                     for (int j = 0; j < 8; ++j) t[j] += sp[64 * j]; }
.LBB0_1756:
	v_lshl_add_u64 v[152:153], v[124:125], 0, s[12:13]
	v_add_co_u32_e32 v164, vcc, 0x3af00000, v152
	v_add_co_u32_e64 v148, s[0:1], s15, v152
	s_nop 0
	v_addc_co_u32_e32 v165, vcc, 0, v153, vcc
	v_addc_co_u32_e64 v149, s[0:1], 0, v153, s[0:1]
	global_load_dwordx4 v[136:139], v[148:149], off
	global_load_dwordx4 v[140:143], v[148:149], off offset:1024
	global_load_dwordx4 v[144:147], v[148:149], off offset:2048
	s_nop 0
	global_load_dwordx4 v[148:151], v[148:149], off offset:3072
	s_nop 0
	global_load_dwordx4 v[152:155], v[164:165], off
	global_load_dwordx4 v[156:159], v[164:165], off offset:1024
	global_load_dwordx4 v[160:163], v[164:165], off offset:2048
	s_nop 0
	global_load_dwordx4 v[164:167], v[164:165], off offset:3072
	s_add_u32 s12, s12, 0x400000
	s_addc_u32 s13, s13, 0
	v_lshl_add_u64 v[184:185], v[124:125], 0, s[12:13]
	v_add_co_u32_e32 v196, vcc, 0x3af00000, v184
	v_add_co_u32_e64 v180, s[0:1], s15, v184
	s_nop 0
	v_addc_co_u32_e32 v197, vcc, 0, v185, vcc
	v_addc_co_u32_e64 v181, s[0:1], 0, v185, s[0:1]
	global_load_dwordx4 v[168:171], v[180:181], off
	global_load_dwordx4 v[172:175], v[180:181], off offset:1024
	global_load_dwordx4 v[176:179], v[180:181], off offset:2048
	s_nop 0
	global_load_dwordx4 v[180:183], v[180:181], off offset:3072
	s_nop 0
	global_load_dwordx4 v[184:187], v[196:197], off
	global_load_dwordx4 v[188:191], v[196:197], off offset:1024
	global_load_dwordx4 v[192:195], v[196:197], off offset:2048
	s_nop 0
	global_load_dwordx4 v[196:199], v[196:197], off offset:3072
	s_add_u32 s12, s12, 0x400000
	s_addc_u32 s13, s13, 0
	v_lshl_add_u64 v[216:217], v[124:125], 0, s[12:13]
	v_add_co_u32_e32 v228, vcc, 0x3af00000, v216
	v_add_co_u32_e64 v212, s[0:1], s15, v216
	s_nop 0
	v_addc_co_u32_e32 v229, vcc, 0, v217, vcc
	v_addc_co_u32_e64 v213, s[0:1], 0, v217, s[0:1]
	global_load_dwordx4 v[200:203], v[212:213], off
	global_load_dwordx4 v[204:207], v[212:213], off offset:1024
	global_load_dwordx4 v[208:211], v[212:213], off offset:2048
	s_nop 0
	global_load_dwordx4 v[212:215], v[212:213], off offset:3072
	s_nop 0
	global_load_dwordx4 v[216:219], v[228:229], off
	global_load_dwordx4 v[220:223], v[228:229], off offset:1024
	global_load_dwordx4 v[224:227], v[228:229], off offset:2048
	s_nop 0
	global_load_dwordx4 v[228:231], v[228:229], off offset:3072
	s_add_u32 s12, s12, 0x400000
	s_addc_u32 s13, s13, 0
	s_waitcnt vmcnt(16)
	v_pk_add_f32 v[84:85], v[84:85], v[138:139]
	v_pk_add_f32 v[82:83], v[82:83], v[136:137]
	v_pk_add_f32 v[76:77], v[76:77], v[142:143]
	v_pk_add_f32 v[74:75], v[74:75], v[140:141]
	v_pk_add_f32 v[72:73], v[72:73], v[146:147]
	v_pk_add_f32 v[70:71], v[70:71], v[144:145]
	v_pk_add_f32 v[68:69], v[68:69], v[150:151]
	v_pk_add_f32 v[66:67], v[66:67], v[148:149]
	v_pk_add_f32 v[92:93], v[92:93], v[154:155]
	v_pk_add_f32 v[90:91], v[90:91], v[152:153]
	v_pk_add_f32 v[96:97], v[96:97], v[158:159]
	v_pk_add_f32 v[94:95], v[94:95], v[156:157]
	v_pk_add_f32 v[88:89], v[88:89], v[162:163]
	v_pk_add_f32 v[86:87], v[86:87], v[160:161]
	v_pk_add_f32 v[80:81], v[80:81], v[166:167]
	v_pk_add_f32 v[78:79], v[78:79], v[164:165]
	s_waitcnt vmcnt(8)
	v_pk_add_f32 v[84:85], v[84:85], v[170:171]
	v_pk_add_f32 v[82:83], v[82:83], v[168:169]
	v_pk_add_f32 v[76:77], v[76:77], v[174:175]
	v_pk_add_f32 v[74:75], v[74:75], v[172:173]
	v_pk_add_f32 v[72:73], v[72:73], v[178:179]
	v_pk_add_f32 v[70:71], v[70:71], v[176:177]
	v_pk_add_f32 v[68:69], v[68:69], v[182:183]
	v_pk_add_f32 v[66:67], v[66:67], v[180:181]
	v_pk_add_f32 v[92:93], v[92:93], v[186:187]
	v_pk_add_f32 v[90:91], v[90:91], v[184:185]
	v_pk_add_f32 v[96:97], v[96:97], v[190:191]
	v_pk_add_f32 v[94:95], v[94:95], v[188:189]
	v_pk_add_f32 v[88:89], v[88:89], v[194:195]
	v_pk_add_f32 v[86:87], v[86:87], v[192:193]
	v_pk_add_f32 v[80:81], v[80:81], v[198:199]
	v_pk_add_f32 v[78:79], v[78:79], v[196:197]
	s_waitcnt vmcnt(0)
; #define GAS __attribute__((address_space(1)))
; __device__ __forceinline__ float bflo(unsigned w) { return __uint_as_float(w << 16); }
; __device__ __forceinline__ float bfhi(unsigned w) { return __uint_as_float(w & 0xffff0000u); }
; __device__ __forceinline__ float sigmf(float x) { return __builtin_amdgcn_rcpf(1.0f + __expf(-x)); }
; __device__ __forceinline__ float dot4(f32x4 a, f32x4 b) { return (a[0] * b[0] + a[1] * b[1]) + (a[2] * b[2] + a[3] * b[3]); }
;     ...
;                 _Pragma("unroll 1") for (int s = 1; s < nslab; ++s) { sp += (size_t)NS * D / 4;
; #pragma unroll
;                     for (int j = 0; j < 8; ++j) t[j] += sp[64 * j]; }
;                 if (TSRC == 2) { const GAS v2u* pp = (const GAS v2u*)(PUP + (size_t)r * D) + lane;
; #pragma unroll
;                     for (int j = 0; j < 8; ++j) { const v2u pw = pp[64 * j]; const f32x4 p = (f32x4){bflo(pw.x), bfhi(pw.x), bflo(pw.y), bfhi(pw.y)}; t[j] = (f32x4){sigmf(t[j][0]), sigmf(t[j][1]), sigmf(t[j][2]), sigmf(t[j][3])} * p; } }
; #pragma unroll
;                 for (int j = 0; j < 8; ++j) ss += dot4(t[j], t[j]);
	v_pk_add_f32 v[84:85], v[84:85], v[202:203]
	v_pk_add_f32 v[82:83], v[82:83], v[200:201]
	v_pk_add_f32 v[76:77], v[76:77], v[206:207]
	v_pk_add_f32 v[74:75], v[74:75], v[204:205]
	v_pk_add_f32 v[72:73], v[72:73], v[210:211]
	v_pk_add_f32 v[70:71], v[70:71], v[208:209]
	v_pk_add_f32 v[68:69], v[68:69], v[214:215]
	v_pk_add_f32 v[66:67], v[66:67], v[212:213]
	v_pk_add_f32 v[92:93], v[92:93], v[218:219]
	v_pk_add_f32 v[90:91], v[90:91], v[216:217]
	v_pk_add_f32 v[96:97], v[96:97], v[222:223]
	v_pk_add_f32 v[94:95], v[94:95], v[220:221]
	v_pk_add_f32 v[88:89], v[88:89], v[226:227]
	v_pk_add_f32 v[86:87], v[86:87], v[224:225]
	v_pk_add_f32 v[80:81], v[80:81], v[230:231]
	v_pk_add_f32 v[78:79], v[78:79], v[228:229]
	s_cmp_lg_u32 s12, 0xc00000
	v_mov_b32_e32 v136, v91
	v_mov_b32_e32 v137, v95
	v_mov_b32_e32 v124, v90
	v_mov_b32_e32 v125, v94
	v_pk_mul_f32 v[136:137], v[136:137], v[136:137]
	v_mov_b32_e32 v138, v93
	v_mov_b32_e32 v139, v97
	v_pk_fma_f32 v[124:125], v[124:125], v[124:125], v[136:137]
	v_mov_b32_e32 v136, v92
	v_mov_b32_e32 v137, v96
	v_pk_mul_f32 v[138:139], v[138:139], v[138:139]
	v_mul_f32_e32 v135, v82, v82
	v_pk_fma_f32 v[136:137], v[136:137], v[136:137], v[138:139]
	v_pk_mul_f32 v[138:139], v[86:87], v[86:87]
	v_pk_add_f32 v[124:125], v[124:125], v[136:137]
	v_pk_mul_f32 v[136:137], v[88:89], v[88:89]
	v_pk_add_f32 v[124:125], v[124:125], v[124:125] op_sel:[0,1] op_sel_hi:[1,0]
	v_pk_mov_b32 v[140:141], v[138:139], v[136:137] op_sel:[1,0]
	v_mov_b32_e32 v139, v137
	v_pk_add_f32 v[136:137], v[140:141], v[138:139]
	v_mul_f32_e32 v138, v83, v83
	v_pk_add_f32 v[136:137], v[136:137], v[136:137] op_sel:[0,1] op_sel_hi:[1,0]
	v_mov_b32_e32 v125, v135
	v_mov_b32_e32 v137, v138
	v_pk_add_f32 v[124:125], v[124:125], v[136:137]
	v_mul_f32_e32 v136, v79, v79
	v_mul_f32_e32 v139, v84, v84
	v_pk_fma_f32 v[136:137], v[78:79], v[78:79], v[136:137] op_sel_hi:[1,1,0]
	v_mul_f32_e32 v138, v81, v81
	v_mul_f32_e32 v140, v85, v85
	v_mov_b32_e32 v137, v139
	v_pk_fma_f32 v[138:139], v[80:81], v[80:81], v[138:139] op_sel_hi:[1,1,0]
	v_mul_f32_e32 v135, v66, v66
	v_mov_b32_e32 v139, v140
	v_pk_add_f32 v[136:137], v[136:137], v[138:139]
	v_pk_mul_f32 v[138:139], v[74:75], v[74:75]
	v_pk_add_f32 v[124:125], v[124:125], v[136:137]
	v_pk_mul_f32 v[136:137], v[76:77], v[76:77]
	v_pk_add_f32 v[124:125], v[124:125], v[124:125] op_sel:[0,1] op_sel_hi:[1,0]
	v_pk_mov_b32 v[140:141], v[138:139], v[136:137] op_sel:[1,0]
	v_mov_b32_e32 v139, v137
	v_pk_add_f32 v[136:137], v[140:141], v[138:139]
	v_mul_f32_e32 v138, v67, v67
	v_pk_add_f32 v[136:137], v[136:137], v[136:137] op_sel:[0,1] op_sel_hi:[1,0]
	v_mov_b32_e32 v125, v135
	v_mov_b32_e32 v137, v138
	v_pk_add_f32 v[124:125], v[124:125], v[136:137]
	v_mul_f32_e32 v136, v71, v71
	v_mul_f32_e32 v139, v68, v68
	v_pk_fma_f32 v[136:137], v[70:71], v[70:71], v[136:137] op_sel_hi:[1,1,0]
	v_mul_f32_e32 v138, v73, v73
	v_mul_f32_e32 v140, v69, v69
	v_mov_b32_e32 v137, v139
	v_pk_fma_f32 v[138:139], v[72:73], v[72:73], v[138:139] op_sel_hi:[1,1,0]
	s_nop 0
	v_mov_b32_e32 v139, v140
	v_pk_add_f32 v[136:137], v[136:137], v[138:139]
	s_nop 0
	v_pk_add_f32 v[124:125], v[124:125], v[136:137]
	s_nop 0
	v_add_f32_e32 v124, v124, v125
	s_branch .LBB0_1751

; #define GAS __attribute__((address_space(1)))
;     ...
;                 const GAS f32x4* sp = (const GAS f32x4*)(WSP(float, WS_SLAB) + (size_t)(r - NP) * D) + lane;
; #pragma unroll
;                 for (int j = 0; j < 8; ++j) t[j] = sp[64 * j];
;                 _Pragma("unroll 1") for (int s = 1; s < nslab; ++s) { sp += (size_t)NS * D / 4;
; #pragma unroll
;                     for (int j = 0; j < 8; ++j) t[j] += sp[64 * j]; }
.LBB0_1903:
	v_lshl_add_u64 v[106:107], v[90:91], 0, s[0:1]
	v_add_co_u32_e32 v122, vcc, s9, v106
	s_add_u32 s0, s0, 0x400000
	s_nop 0
	v_addc_co_u32_e32 v123, vcc, 0, v107, vcc
	v_add_co_u32_e32 v134, vcc, s10, v106
	s_addc_u32 s1, s1, 0
	s_nop 0
	v_addc_co_u32_e32 v135, vcc, 0, v107, vcc
	global_load_dwordx4 v[106:109], v[134:135], off offset:-4096
	global_load_dwordx4 v[110:113], v[122:123], off offset:1024
	global_load_dwordx4 v[114:117], v[122:123], off offset:2048
	global_load_dwordx4 v[118:121], v[122:123], off offset:3072
	s_nop 0
	global_load_dwordx4 v[122:125], v[134:135], off
	global_load_dwordx4 v[126:129], v[134:135], off offset:1024
	global_load_dwordx4 v[130:133], v[134:135], off offset:2048
	s_nop 0
	global_load_dwordx4 v[134:137], v[134:135], off offset:3072
	v_lshl_add_u64 v[138:139], v[90:91], 0, s[0:1]
	v_add_co_u32_e32 v154, vcc, s9, v138
	s_add_u32 s0, s0, 0x400000
	s_nop 0
	v_addc_co_u32_e32 v155, vcc, 0, v139, vcc
	v_add_co_u32_e32 v166, vcc, s10, v138
	s_addc_u32 s1, s1, 0
	s_nop 0
	v_addc_co_u32_e32 v167, vcc, 0, v139, vcc
	global_load_dwordx4 v[138:141], v[166:167], off offset:-4096
	global_load_dwordx4 v[142:145], v[154:155], off offset:1024
	global_load_dwordx4 v[146:149], v[154:155], off offset:2048
	global_load_dwordx4 v[150:153], v[154:155], off offset:3072
	s_nop 0
	global_load_dwordx4 v[154:157], v[166:167], off
	global_load_dwordx4 v[158:161], v[166:167], off offset:1024
	global_load_dwordx4 v[162:165], v[166:167], off offset:2048
	s_nop 0
	global_load_dwordx4 v[166:169], v[166:167], off offset:3072
	v_lshl_add_u64 v[170:171], v[90:91], 0, s[0:1]
	v_add_co_u32_e32 v186, vcc, s9, v170
	s_add_u32 s0, s0, 0x400000
	s_nop 0
	v_addc_co_u32_e32 v187, vcc, 0, v171, vcc
	v_add_co_u32_e32 v198, vcc, s10, v170
	s_addc_u32 s1, s1, 0
	s_nop 0
	v_addc_co_u32_e32 v199, vcc, 0, v171, vcc
	global_load_dwordx4 v[170:173], v[198:199], off offset:-4096
	global_load_dwordx4 v[174:177], v[186:187], off offset:1024
	global_load_dwordx4 v[178:181], v[186:187], off offset:2048
	global_load_dwordx4 v[182:185], v[186:187], off offset:3072
	s_nop 0
	global_load_dwordx4 v[186:189], v[198:199], off
	global_load_dwordx4 v[190:193], v[198:199], off offset:1024
	global_load_dwordx4 v[194:197], v[198:199], off offset:2048
	s_nop 0
	global_load_dwordx4 v[198:201], v[198:199], off offset:3072
	v_lshl_add_u64 v[202:203], v[90:91], 0, s[0:1]
	v_add_co_u32_e32 v218, vcc, s9, v202
	s_add_u32 s0, s0, 0x400000
	s_nop 0
	v_addc_co_u32_e32 v219, vcc, 0, v203, vcc
	v_add_co_u32_e32 v230, vcc, s10, v202
	s_addc_u32 s1, s1, 0
	s_nop 0
	v_addc_co_u32_e32 v231, vcc, 0, v203, vcc
	global_load_dwordx4 v[202:205], v[230:231], off offset:-4096
	global_load_dwordx4 v[206:209], v[218:219], off offset:1024
	global_load_dwordx4 v[210:213], v[218:219], off offset:2048
	global_load_dwordx4 v[214:217], v[218:219], off offset:3072
	s_nop 0
	global_load_dwordx4 v[218:221], v[230:231], off
	global_load_dwordx4 v[222:225], v[230:231], off offset:1024
	global_load_dwordx4 v[226:229], v[230:231], off offset:2048
	s_nop 0
	global_load_dwordx4 v[230:233], v[230:231], off offset:3072
	s_waitcnt vmcnt(24)
	v_pk_add_f32 v[62:63], v[62:63], v[108:109]
	v_pk_add_f32 v[60:61], v[60:61], v[106:107]
	v_pk_add_f32 v[58:59], v[58:59], v[112:113]
	v_pk_add_f32 v[56:57], v[56:57], v[110:111]
	v_pk_add_f32 v[54:55], v[54:55], v[116:117]
	v_pk_add_f32 v[52:53], v[52:53], v[114:115]
	v_pk_add_f32 v[50:51], v[50:51], v[120:121]
	v_pk_add_f32 v[48:49], v[48:49], v[118:119]
	v_pk_add_f32 v[46:47], v[46:47], v[124:125]
	v_pk_add_f32 v[44:45], v[44:45], v[122:123]
	v_pk_add_f32 v[42:43], v[42:43], v[128:129]
	v_pk_add_f32 v[40:41], v[40:41], v[126:127]
	v_pk_add_f32 v[38:39], v[38:39], v[132:133]
	v_pk_add_f32 v[36:37], v[36:37], v[130:131]
	v_pk_add_f32 v[34:35], v[34:35], v[136:137]
	v_pk_add_f32 v[32:33], v[32:33], v[134:135]
	v_lshl_add_u64 v[106:107], v[90:91], 0, s[0:1]
	v_add_co_u32_e32 v122, vcc, s9, v106
	s_add_u32 s0, s0, 0x400000
	s_nop 0
	v_addc_co_u32_e32 v123, vcc, 0, v107, vcc
	v_add_co_u32_e32 v134, vcc, s10, v106
	s_addc_u32 s1, s1, 0
	s_nop 0
	v_addc_co_u32_e32 v135, vcc, 0, v107, vcc
	global_load_dwordx4 v[106:109], v[134:135], off offset:-4096
	global_load_dwordx4 v[110:113], v[122:123], off offset:1024
	global_load_dwordx4 v[114:117], v[122:123], off offset:2048
	global_load_dwordx4 v[118:121], v[122:123], off offset:3072
	s_nop 0
	global_load_dwordx4 v[122:125], v[134:135], off
	global_load_dwordx4 v[126:129], v[134:135], off offset:1024
	global_load_dwordx4 v[130:133], v[134:135], off offset:2048
	s_nop 0
	global_load_dwordx4 v[134:137], v[134:135], off offset:3072
	s_waitcnt vmcnt(24)
	v_pk_add_f32 v[62:63], v[62:63], v[140:141]
	v_pk_add_f32 v[60:61], v[60:61], v[138:139]
	v_pk_add_f32 v[58:59], v[58:59], v[144:145]
	v_pk_add_f32 v[56:57], v[56:57], v[142:143]
	v_pk_add_f32 v[54:55], v[54:55], v[148:149]
	v_pk_add_f32 v[52:53], v[52:53], v[146:147]
	v_pk_add_f32 v[50:51], v[50:51], v[152:153]
	v_pk_add_f32 v[48:49], v[48:49], v[150:151]
	v_pk_add_f32 v[46:47], v[46:47], v[156:157]
	v_pk_add_f32 v[44:45], v[44:45], v[154:155]
	v_pk_add_f32 v[42:43], v[42:43], v[160:161]
	v_pk_add_f32 v[40:41], v[40:41], v[158:159]
	v_pk_add_f32 v[38:39], v[38:39], v[164:165]
	v_pk_add_f32 v[36:37], v[36:37], v[162:163]
	v_pk_add_f32 v[34:35], v[34:35], v[168:169]
	v_pk_add_f32 v[32:33], v[32:33], v[166:167]
	v_lshl_add_u64 v[138:139], v[90:91], 0, s[0:1]
	v_add_co_u32_e32 v154, vcc, s9, v138
	s_add_u32 s0, s0, 0x400000
	s_nop 0
	v_addc_co_u32_e32 v155, vcc, 0, v139, vcc
	v_add_co_u32_e32 v166, vcc, s10, v138
	s_addc_u32 s1, s1, 0
	s_nop 0
	v_addc_co_u32_e32 v167, vcc, 0, v139, vcc
	global_load_dwordx4 v[138:141], v[166:167], off offset:-4096
	global_load_dwordx4 v[142:145], v[154:155], off offset:1024
	global_load_dwordx4 v[146:149], v[154:155], off offset:2048
	global_load_dwordx4 v[150:153], v[154:155], off offset:3072
	s_nop 0
	global_load_dwordx4 v[154:157], v[166:167], off
	global_load_dwordx4 v[158:161], v[166:167], off offset:1024
	global_load_dwordx4 v[162:165], v[166:167], off offset:2048
	s_nop 0
	global_load_dwordx4 v[166:169], v[166:167], off offset:3072
	s_waitcnt vmcnt(24)
; #define GAS __attribute__((address_space(1)))
; __device__ __forceinline__ float bflo(unsigned w) { return __uint_as_float(w << 16); }
; __device__ __forceinline__ float bfhi(unsigned w) { return __uint_as_float(w & 0xffff0000u); }
; __device__ __forceinline__ float sigmf(float x) { return __builtin_amdgcn_rcpf(1.0f + __expf(-x)); }
;     ...
;                 _Pragma("unroll 1") for (int s = 1; s < nslab; ++s) { sp += (size_t)NS * D / 4;
; #pragma unroll
;                     for (int j = 0; j < 8; ++j) t[j] += sp[64 * j]; }
;                 if (TSRC == 2) { const GAS v2u* pp = (const GAS v2u*)(PUP + (size_t)r * D) + lane;
; #pragma unroll
;                     for (int j = 0; j < 8; ++j) { const v2u pw = pp[64 * j]; const f32x4 p = (f32x4){bflo(pw.x), bfhi(pw.x), bflo(pw.y), bfhi(pw.y)}; t[j] = (f32x4){sigmf(t[j][0]), sigmf(t[j][1]), sigmf(t[j][2]), sigmf(t[j][3])} * p; } }
	v_pk_add_f32 v[62:63], v[62:63], v[172:173]
	v_pk_add_f32 v[60:61], v[60:61], v[170:171]
	v_pk_add_f32 v[58:59], v[58:59], v[176:177]
	v_pk_add_f32 v[56:57], v[56:57], v[174:175]
	v_pk_add_f32 v[54:55], v[54:55], v[180:181]
	v_pk_add_f32 v[52:53], v[52:53], v[178:179]
	v_pk_add_f32 v[50:51], v[50:51], v[184:185]
	v_pk_add_f32 v[48:49], v[48:49], v[182:183]
	v_pk_add_f32 v[46:47], v[46:47], v[188:189]
	v_pk_add_f32 v[44:45], v[44:45], v[186:187]
	v_pk_add_f32 v[42:43], v[42:43], v[192:193]
	v_pk_add_f32 v[40:41], v[40:41], v[190:191]
	v_pk_add_f32 v[38:39], v[38:39], v[196:197]
	v_pk_add_f32 v[36:37], v[36:37], v[194:195]
	v_pk_add_f32 v[34:35], v[34:35], v[200:201]
	v_pk_add_f32 v[32:33], v[32:33], v[198:199]
	v_lshl_add_u64 v[170:171], v[90:91], 0, s[0:1]
	v_add_co_u32_e32 v186, vcc, s9, v170
	s_add_u32 s0, s0, 0x400000
	s_nop 0
	v_addc_co_u32_e32 v187, vcc, 0, v171, vcc
	v_add_co_u32_e32 v198, vcc, s10, v170
	s_addc_u32 s1, s1, 0
	s_nop 0
	v_addc_co_u32_e32 v199, vcc, 0, v171, vcc
	global_load_dwordx4 v[170:173], v[198:199], off offset:-4096
	global_load_dwordx4 v[174:177], v[186:187], off offset:1024
	global_load_dwordx4 v[178:181], v[186:187], off offset:2048
	global_load_dwordx4 v[182:185], v[186:187], off offset:3072
	s_nop 0
	global_load_dwordx4 v[186:189], v[198:199], off
	global_load_dwordx4 v[190:193], v[198:199], off offset:1024
	global_load_dwordx4 v[194:197], v[198:199], off offset:2048
	s_nop 0
	global_load_dwordx4 v[198:201], v[198:199], off offset:3072
	s_waitcnt vmcnt(24)
	v_pk_add_f32 v[62:63], v[62:63], v[204:205]
	v_pk_add_f32 v[60:61], v[60:61], v[202:203]
	v_pk_add_f32 v[58:59], v[58:59], v[208:209]
	v_pk_add_f32 v[56:57], v[56:57], v[206:207]
	v_pk_add_f32 v[54:55], v[54:55], v[212:213]
	v_pk_add_f32 v[52:53], v[52:53], v[210:211]
	v_pk_add_f32 v[50:51], v[50:51], v[216:217]
	v_pk_add_f32 v[48:49], v[48:49], v[214:215]
	v_pk_add_f32 v[46:47], v[46:47], v[220:221]
	v_pk_add_f32 v[44:45], v[44:45], v[218:219]
	v_pk_add_f32 v[42:43], v[42:43], v[224:225]
	v_pk_add_f32 v[40:41], v[40:41], v[222:223]
	v_pk_add_f32 v[38:39], v[38:39], v[228:229]
	v_pk_add_f32 v[36:37], v[36:37], v[226:227]
	v_pk_add_f32 v[34:35], v[34:35], v[232:233]
	v_pk_add_f32 v[32:33], v[32:33], v[230:231]
	s_waitcnt vmcnt(16)
	v_pk_add_f32 v[62:63], v[62:63], v[108:109]
	v_pk_add_f32 v[60:61], v[60:61], v[106:107]
	v_pk_add_f32 v[58:59], v[58:59], v[112:113]
	v_pk_add_f32 v[56:57], v[56:57], v[110:111]
	v_pk_add_f32 v[54:55], v[54:55], v[116:117]
	v_pk_add_f32 v[52:53], v[52:53], v[114:115]
	v_pk_add_f32 v[50:51], v[50:51], v[120:121]
	v_pk_add_f32 v[48:49], v[48:49], v[118:119]
	v_pk_add_f32 v[46:47], v[46:47], v[124:125]
	v_pk_add_f32 v[44:45], v[44:45], v[122:123]
	v_pk_add_f32 v[42:43], v[42:43], v[128:129]
	v_pk_add_f32 v[40:41], v[40:41], v[126:127]
	v_pk_add_f32 v[38:39], v[38:39], v[132:133]
	v_pk_add_f32 v[36:37], v[36:37], v[130:131]
	v_pk_add_f32 v[34:35], v[34:35], v[136:137]
	v_pk_add_f32 v[32:33], v[32:33], v[134:135]
	s_waitcnt vmcnt(8)
	v_pk_add_f32 v[62:63], v[62:63], v[140:141]
	v_pk_add_f32 v[60:61], v[60:61], v[138:139]
	v_pk_add_f32 v[58:59], v[58:59], v[144:145]
	v_pk_add_f32 v[56:57], v[56:57], v[142:143]
	v_pk_add_f32 v[54:55], v[54:55], v[148:149]
	v_pk_add_f32 v[52:53], v[52:53], v[146:147]
	v_pk_add_f32 v[50:51], v[50:51], v[152:153]
	v_pk_add_f32 v[48:49], v[48:49], v[150:151]
	v_pk_add_f32 v[46:47], v[46:47], v[156:157]
	v_pk_add_f32 v[44:45], v[44:45], v[154:155]
	v_pk_add_f32 v[42:43], v[42:43], v[160:161]
	v_pk_add_f32 v[40:41], v[40:41], v[158:159]
	v_pk_add_f32 v[38:39], v[38:39], v[164:165]
	v_pk_add_f32 v[36:37], v[36:37], v[162:163]
	v_pk_add_f32 v[34:35], v[34:35], v[168:169]
	v_pk_add_f32 v[32:33], v[32:33], v[166:167]
	s_waitcnt vmcnt(0)
	v_pk_add_f32 v[62:63], v[62:63], v[172:173]
	v_pk_add_f32 v[60:61], v[60:61], v[170:171]
	v_pk_add_f32 v[58:59], v[58:59], v[176:177]
	v_pk_add_f32 v[56:57], v[56:57], v[174:175]
	v_pk_add_f32 v[54:55], v[54:55], v[180:181]
	v_pk_add_f32 v[52:53], v[52:53], v[178:179]
	v_pk_add_f32 v[50:51], v[50:51], v[184:185]
	v_pk_add_f32 v[48:49], v[48:49], v[182:183]
	v_pk_add_f32 v[46:47], v[46:47], v[188:189]
	v_pk_add_f32 v[44:45], v[44:45], v[186:187]
	v_pk_add_f32 v[42:43], v[42:43], v[192:193]
	v_pk_add_f32 v[40:41], v[40:41], v[190:191]
	v_pk_add_f32 v[38:39], v[38:39], v[196:197]
	v_pk_add_f32 v[36:37], v[36:37], v[194:195]
	v_pk_add_f32 v[34:35], v[34:35], v[200:201]
	v_pk_add_f32 v[32:33], v[32:33], v[198:199]
	s_cmp_eq_u32 s0, 0x1c00000
	v_lshl_add_u64 v[90:91], s[6:7], 1, v[72:73]
	global_load_dwordx2 v[106:107], v[90:91], off
	global_load_dwordx2 v[108:109], v[90:91], off offset:512
	global_load_dwordx2 v[110:111], v[90:91], off offset:1024
	global_load_dwordx2 v[112:113], v[90:91], off offset:1536
	global_load_dwordx2 v[114:115], v[90:91], off offset:2048
	global_load_dwordx2 v[116:117], v[90:91], off offset:2560
	global_load_dwordx2 v[118:119], v[90:91], off offset:3072
	v_mul_f32_e32 v56, 0xbfb8aa3b, v56
	global_load_dwordx2 v[90:91], v[90:91], off offset:3584
	v_mul_f32_e32 v57, 0xbfb8aa3b, v57
	v_mul_f32_e32 v58, 0xbfb8aa3b, v58
	v_mul_f32_e32 v59, 0xbfb8aa3b, v59
	v_mul_f32_e32 v54, 0xbfb8aa3b, v54
	v_mul_f32_e32 v55, 0xbfb8aa3b, v55
	v_exp_f32_e32 v56, v56
	v_exp_f32_e32 v57, v57
	v_exp_f32_e32 v58, v58
	v_exp_f32_e32 v59, v59
	v_exp_f32_e32 v54, v54
	v_exp_f32_e32 v55, v55
	v_mul_f32_e32 v60, 0xbfb8aa3b, v60
	v_mul_f32_e32 v61, 0xbfb8aa3b, v61
	v_mul_f32_e32 v62, 0xbfb8aa3b, v62
	v_mul_f32_e32 v63, 0xbfb8aa3b, v63
	v_mul_f32_e32 v52, 0xbfb8aa3b, v52
	v_mul_f32_e32 v53, 0xbfb8aa3b, v53
	v_mul_f32_e32 v105, 0xbfb8aa3b, v49
	v_exp_f32_e32 v49, v60
	v_exp_f32_e32 v60, v61
; #define GAS __attribute__((address_space(1)))
; __device__ __forceinline__ float bflo(unsigned w) { return __uint_as_float(w << 16); }
; __device__ __forceinline__ float bfhi(unsigned w) { return __uint_as_float(w & 0xffff0000u); }
; __device__ __forceinline__ float sigmf(float x) { return __builtin_amdgcn_rcpf(1.0f + __expf(-x)); }
; __device__ __forceinline__ float dot4(f32x4 a, f32x4 b) { return (a[0] * b[0] + a[1] * b[1]) + (a[2] * b[2] + a[3] * b[3]); }
;     ...
;                 if (TSRC == 2) { const GAS v2u* pp = (const GAS v2u*)(PUP + (size_t)r * D) + lane;
; #pragma unroll
;                     for (int j = 0; j < 8; ++j) { const v2u pw = pp[64 * j]; const f32x4 p = (f32x4){bflo(pw.x), bfhi(pw.x), bflo(pw.y), bfhi(pw.y)}; t[j] = (f32x4){sigmf(t[j][0]), sigmf(t[j][1]), sigmf(t[j][2]), sigmf(t[j][3])} * p; } }
; #pragma unroll
;                 for (int j = 0; j < 8; ++j) ss += dot4(t[j], t[j]);
	v_exp_f32_e32 v61, v62
	v_exp_f32_e32 v62, v63
	v_exp_f32_e32 v52, v52
	v_exp_f32_e32 v53, v53
	v_add_f32_e32 v56, 1.0, v56
	v_add_f32_e32 v57, 1.0, v57
	v_add_f32_e32 v58, 1.0, v58
	v_add_f32_e32 v59, 1.0, v59
	v_mul_f32_e32 v36, 0xbfb8aa3b, v36
	v_add_f32_e32 v122, 1.0, v54
	v_add_f32_e32 v123, 1.0, v55
	v_rcp_f32_e32 v54, v56
	v_rcp_f32_e32 v55, v57
	v_rcp_f32_e32 v56, v58
	v_rcp_f32_e32 v57, v59
	v_exp_f32_e32 v36, v36
	v_add_f32_e32 v62, 1.0, v62
	v_add_f32_e32 v63, 1.0, v52
	v_mul_f32_e32 v46, 0xbfb8aa3b, v46
	v_mul_f32_e32 v47, 0xbfb8aa3b, v47
	v_add_f32_e32 v121, 1.0, v53
	v_rcp_f32_e32 v53, v62
	v_rcp_f32_e32 v120, v63
	v_exp_f32_e32 v46, v46
	v_exp_f32_e32 v47, v47
	v_mul_f32_e32 v42, 0xbfb8aa3b, v42
	v_mul_f32_e32 v43, 0xbfb8aa3b, v43
	v_exp_f32_e32 v42, v42
	v_exp_f32_e32 v43, v43
	v_mul_f32_e32 v48, 0xbfb8aa3b, v48
	v_exp_f32_e32 v48, v48
	v_add_f32_e32 v61, 1.0, v61
	v_rcp_f32_e32 v52, v61
	v_rcp_f32_e32 v121, v121
	v_add_f32_e32 v46, 1.0, v46
	v_add_f32_e32 v47, 1.0, v47
	v_rcp_f32_e32 v46, v46
	v_rcp_f32_e32 v47, v47
	v_add_f32_e32 v42, 1.0, v42
	v_add_f32_e32 v43, 1.0, v43
	v_mul_f32_e32 v32, 0xbfb8aa3b, v32
	v_add_f32_e32 v49, 1.0, v49
	v_add_f32_e32 v60, 1.0, v60
	v_rcp_f32_e32 v42, v42
	v_rcp_f32_e32 v43, v43
	v_exp_f32_e32 v32, v32
	v_add_f32_e32 v126, 1.0, v48
	v_rcp_f32_e32 v48, v49
	v_rcp_f32_e32 v49, v60
	v_mul_f32_e32 v44, 0xbfb8aa3b, v44
	v_mul_f32_e32 v45, 0xbfb8aa3b, v45
	v_exp_f32_e32 v44, v44
	s_waitcnt vmcnt(7)
	v_lshlrev_b32_e32 v60, 16, v106
	s_waitcnt vmcnt(6)
	v_lshlrev_b32_e32 v62, 16, v109
	v_and_b32_e32 v63, 0xffff0000, v109
	v_pk_mul_f32 v[62:63], v[56:57], v[62:63]
	v_exp_f32_e32 v57, v105
	v_add_f32_e32 v105, 1.0, v36
	v_mul_f32_e32 v36, 0xbfb8aa3b, v37
	v_mul_f32_e32 v37, 0xbfb8aa3b, v38
	v_mul_f32_e32 v38, 0xbfb8aa3b, v39
	v_exp_f32_e32 v37, v37
	v_exp_f32_e32 v38, v38
	v_exp_f32_e32 v39, v36
	v_and_b32_e32 v61, 0xffff0000, v106
	v_add_f32_e32 v36, 1.0, v37
	v_add_f32_e32 v37, 1.0, v38
	v_lshlrev_b32_e32 v58, 16, v107
	v_and_b32_e32 v59, 0xffff0000, v107
	v_lshlrev_b32_e32 v106, 16, v108
	v_and_b32_e32 v107, 0xffff0000, v108
	s_waitcnt vmcnt(5)
	v_lshlrev_b32_e32 v108, 16, v110
	v_and_b32_e32 v109, 0xffff0000, v110
	v_rcp_f32_e32 v36, v36
	v_rcp_f32_e32 v37, v37
	v_pk_mul_f32 v[58:59], v[52:53], v[58:59]
	v_pk_mul_f32 v[52:53], v[120:121], v[108:109]
	s_waitcnt vmcnt(3)
	v_lshlrev_b32_e32 v108, 16, v115
	v_and_b32_e32 v109, 0xffff0000, v115
	v_exp_f32_e32 v45, v45
	v_pk_mul_f32 v[46:47], v[46:47], v[108:109]
	v_mul_f32_e32 v40, 0xbfb8aa3b, v40
	v_mul_f32_e32 v41, 0xbfb8aa3b, v41
	s_waitcnt vmcnt(2)
	v_lshlrev_b32_e32 v108, 16, v117
	v_and_b32_e32 v109, 0xffff0000, v117
	v_exp_f32_e32 v40, v40
	v_exp_f32_e32 v41, v41
	v_pk_mul_f32 v[42:43], v[42:43], v[108:109]
	s_waitcnt vmcnt(1)
	v_lshlrev_b32_e32 v108, 16, v119
	v_and_b32_e32 v109, 0xffff0000, v119
	v_add_f32_e32 v32, 1.0, v32
	v_pk_mul_f32 v[36:37], v[36:37], v[108:109]
	v_rcp_f32_e32 v108, v32
	v_mul_f32_e32 v32, 0xbfb8aa3b, v33
	v_mul_f32_e32 v33, 0xbfb8aa3b, v34
	v_mul_f32_e32 v34, 0xbfb8aa3b, v35
	v_exp_f32_e32 v32, v32
	v_exp_f32_e32 v33, v33
	v_exp_f32_e32 v34, v34
	v_add_f32_e32 v44, 1.0, v44
	v_add_f32_e32 v45, 1.0, v45
	v_rcp_f32_e32 v44, v44
	v_rcp_f32_e32 v45, v45
	v_add_f32_e32 v40, 1.0, v40
	v_add_f32_e32 v41, 1.0, v41
	v_rcp_f32_e32 v40, v40
	v_rcp_f32_e32 v41, v41
	v_add_f32_e32 v39, 1.0, v39
	v_rcp_f32_e32 v38, v105
	v_rcp_f32_e32 v39, v39
	v_add_f32_e32 v35, 1.0, v32
	v_add_f32_e32 v32, 1.0, v33
	v_add_f32_e32 v33, 1.0, v34
	v_pk_mul_f32 v[54:55], v[54:55], v[106:107]
	v_lshlrev_b32_e32 v106, 16, v114
	v_and_b32_e32 v107, 0xffff0000, v114
	v_rcp_f32_e32 v32, v32
	v_rcp_f32_e32 v33, v33
	v_rcp_f32_e32 v109, v35
	v_pk_mul_f32 v[44:45], v[44:45], v[106:107]
	v_lshlrev_b32_e32 v106, 16, v116
	v_and_b32_e32 v107, 0xffff0000, v116
	v_pk_mul_f32 v[40:41], v[40:41], v[106:107]
	v_lshlrev_b32_e32 v106, 16, v118
	v_and_b32_e32 v107, 0xffff0000, v118
	v_mul_f32_e32 v50, 0xbfb8aa3b, v50
	v_rcp_f32_e32 v122, v122
	v_rcp_f32_e32 v123, v123
	v_pk_mul_f32 v[60:61], v[48:49], v[60:61]
	v_mul_f32_e32 v51, 0xbfb8aa3b, v51
	v_pk_mul_f32 v[38:39], v[38:39], v[106:107]
	s_waitcnt vmcnt(0)
; __device__ __forceinline__ float bflo(unsigned w) { return __uint_as_float(w << 16); }
; __device__ __forceinline__ float bfhi(unsigned w) { return __uint_as_float(w & 0xffff0000u); }
; __device__ __forceinline__ float sigmf(float x) { return __builtin_amdgcn_rcpf(1.0f + __expf(-x)); }
; __device__ __forceinline__ float dot4(f32x4 a, f32x4 b) { return (a[0] * b[0] + a[1] * b[1]) + (a[2] * b[2] + a[3] * b[3]); }
;     ...
;                     for (int j = 0; j < 8; ++j) { const v2u pw = pp[64 * j]; const f32x4 p = (f32x4){bflo(pw.x), bfhi(pw.x), bflo(pw.y), bfhi(pw.y)}; t[j] = (f32x4){sigmf(t[j][0]), sigmf(t[j][1]), sigmf(t[j][2]), sigmf(t[j][3])} * p; } }
; #pragma unroll
;                 for (int j = 0; j < 8; ++j) ss += dot4(t[j], t[j]);
	v_lshlrev_b32_e32 v106, 16, v90
	v_and_b32_e32 v107, 0xffff0000, v90
	v_lshlrev_b32_e32 v34, 16, v91
	v_and_b32_e32 v35, 0xffff0000, v91
	v_exp_f32_e32 v50, v50
	v_exp_f32_e32 v51, v51
	v_pk_mul_f32 v[32:33], v[32:33], v[34:35]
	v_pk_mul_f32 v[34:35], v[108:109], v[106:107]
	v_mov_b32_e32 v106, v61
	v_mov_b32_e32 v107, v55
	v_mov_b32_e32 v90, v60
	v_mov_b32_e32 v91, v54
	v_pk_mul_f32 v[106:107], v[106:107], v[106:107]
	v_mov_b32_e32 v108, v59
	v_mov_b32_e32 v109, v63
	v_lshlrev_b32_e32 v110, 16, v111
	v_and_b32_e32 v111, 0xffff0000, v111
	v_pk_fma_f32 v[90:91], v[90:91], v[90:91], v[106:107]
	v_mov_b32_e32 v106, v58
	v_mov_b32_e32 v107, v62
	v_pk_mul_f32 v[108:109], v[108:109], v[108:109]
	v_pk_mul_f32 v[48:49], v[122:123], v[110:111]
	v_add_f32_e32 v57, 1.0, v57
	v_pk_fma_f32 v[106:107], v[106:107], v[106:107], v[108:109]
	v_add_f32_e32 v50, 1.0, v50
	v_add_f32_e32 v51, 1.0, v51
	v_rcp_f32_e32 v56, v126
	v_rcp_f32_e32 v57, v57
	v_pk_add_f32 v[90:91], v[90:91], v[106:107]
	v_pk_mul_f32 v[106:107], v[48:49], v[48:49]
	v_pk_mul_f32 v[108:109], v[52:53], v[52:53]
	v_rcp_f32_e32 v50, v50
	v_rcp_f32_e32 v51, v51
	v_pk_mov_b32 v[110:111], v[108:109], v[106:107] op_sel:[1,0]
	v_mov_b32_e32 v109, v107
	v_pk_add_f32 v[106:107], v[110:111], v[108:109]
	v_lshlrev_b32_e32 v124, 16, v112
	v_and_b32_e32 v125, 0xffff0000, v112
	v_mul_f32_e32 v105, v44, v44
	v_mul_f32_e32 v108, v45, v45
	v_pk_add_f32 v[90:91], v[90:91], v[90:91] op_sel:[0,1] op_sel_hi:[1,0]
	v_pk_add_f32 v[106:107], v[106:107], v[106:107] op_sel:[0,1] op_sel_hi:[1,0]
	v_lshlrev_b32_e32 v112, 16, v113
	v_and_b32_e32 v113, 0xffff0000, v113
	v_pk_mul_f32 v[56:57], v[56:57], v[124:125]
	v_mov_b32_e32 v91, v105
	v_mov_b32_e32 v107, v108
	v_pk_mul_f32 v[50:51], v[50:51], v[112:113]
	v_pk_add_f32 v[90:91], v[90:91], v[106:107]
	v_mul_f32_e32 v106, v57, v57
	v_mul_f32_e32 v109, v46, v46
	v_pk_fma_f32 v[106:107], v[56:57], v[56:57], v[106:107] op_sel_hi:[1,1,0]
	v_mul_f32_e32 v108, v51, v51
	v_mul_f32_e32 v110, v47, v47
	v_mov_b32_e32 v107, v109
	v_pk_fma_f32 v[108:109], v[50:51], v[50:51], v[108:109] op_sel_hi:[1,1,0]
	v_mul_f32_e32 v105, v34, v34
	v_mov_b32_e32 v109, v110
	v_pk_add_f32 v[106:107], v[106:107], v[108:109]
	v_pk_mul_f32 v[108:109], v[40:41], v[40:41]
	v_pk_add_f32 v[90:91], v[90:91], v[106:107]
	v_pk_mul_f32 v[106:107], v[42:43], v[42:43]
	v_pk_add_f32 v[90:91], v[90:91], v[90:91] op_sel:[0,1] op_sel_hi:[1,0]
	v_pk_mov_b32 v[110:111], v[108:109], v[106:107] op_sel:[1,0]
	v_mov_b32_e32 v109, v107
	v_pk_add_f32 v[106:107], v[110:111], v[108:109]
	v_mul_f32_e32 v108, v35, v35
	v_pk_add_f32 v[106:107], v[106:107], v[106:107] op_sel:[0,1] op_sel_hi:[1,0]
	v_mov_b32_e32 v91, v105
	v_mov_b32_e32 v107, v108
	v_pk_add_f32 v[90:91], v[90:91], v[106:107]
	v_mul_f32_e32 v106, v39, v39
	v_mul_f32_e32 v109, v32, v32
	v_pk_fma_f32 v[106:107], v[38:39], v[38:39], v[106:107] op_sel_hi:[1,1,0]
	v_mul_f32_e32 v108, v37, v37
	v_mul_f32_e32 v110, v33, v33
	v_mov_b32_e32 v107, v109
	v_pk_fma_f32 v[108:109], v[36:37], v[36:37], v[108:109] op_sel_hi:[1,1,0]
	s_nop 0
	v_mov_b32_e32 v109, v110
	v_pk_add_f32 v[106:107], v[106:107], v[108:109]
	s_nop 0
	v_pk_add_f32 v[90:91], v[90:91], v[106:107]
	s_nop 0
	v_add_f32_e32 v90, v90, v91
	s_branch .LBB0_1898
